# P3 chunk-state x^T loads batched + B^T loads hoisted; P5 head loop specialised per token block with prev-state and x^T fragments prefetched one head ahead, decay and dt tables merged into one exponent
# speedup vs baseline: 1.0062x; 1.0015x over previous
; #define LAS __attribute__((address_space(3)))
; __device__ __forceinline__ void chunk_cumsum(const float* DT, const float* a_log, int tok0, int hh, int lane, float& d0, float& d1, float& c0, float& c1, float& tot) {
;     d0 = DT[(size_t)(tok0 + 2 * lane) * 32 + hh]; d1 = DT[(size_t)(tok0 + 2 * lane + 1) * 32 + hh];
;     const float A = -__expf(a_log[hh]); const float x0 = d0 * A, x1 = d1 * A; float ps = x0 + x1;
; #pragma unroll
;     for (int o = 1; o < 64; o <<= 1) { const float t = __shfl_up(ps, o); if (lane >= o) ps += t; }
;     c1 = ps; c0 = ps - x1; tot = __shfl(ps, 63);
; __device__ __forceinline__ void phase_mix(const PT& p, LAS unsigned char* lds, int tid, int lane, int wave) {
;     ...
;             const int id = it - NG, b = id / 60, c = (id / 4) % 15, grp = id & 3; const int bc = b * 16 + c, tok0 = bc * 128;
;             __syncthreads();
;             { const int hh = grp * 8 + wave; float d0, d1, c0, c1, tot; chunk_cumsum(DT, p.in[10], tok0, hh, lane, d0, d1, c0, c1, tot);
;               wtab[wave * 128 + 2 * lane] = d0 * __expf(tot - c0); wtab[wave * 128 + 2 * lane + 1] = d1 * __expf(tot - c1);
;               if (lane == 0) CD[bc * 32 + hh] = __expf(tot); }
; #pragma unroll
;             for (int i = 0; i < 4; ++i) { const int pid = tid + 512 * i, row = pid >> 4, c16 = pid & 15;
;                 *(LAS u32x4*)(lds + ST_BOFF + row * 272 + 16 * c16) = *(const u32x4*)(BT + ((size_t)bc * 512 + grp * 128 + row) * 128 + 8 * c16); }
.LBB0_336:
	s_cmpk_gt_i32 s58, 0x7ff
	s_mov_b64 s[12:13], -1
	s_cbranch_scc0 .LBB0_341
	s_bfe_u32 s14, s58, 0x80002
	s_add_i32 s12, s58, 0xf800
	s_mulk_i32 s14, 0x89
	s_and_b32 s12, s12, 0xffff
	s_lshr_b32 s14, s14, 11
	s_mul_i32 s12, s12, 0x8889
	s_lshr_b32 s13, s58, 2
	s_mul_i32 s14, s14, 15
	s_barrier
	ds_read_b64 v[2:3], v135
	s_sub_i32 s13, s13, s14
	s_and_b32 s24, s58, 3
	s_lshr_b32 s12, s12, 17
	s_and_b32 s13, s13, 0xff
	s_and_b32 s12, s12, 0x7ff0
	s_lshl_b32 s52, s24, 3
	s_or_b32 s59, s12, s13
	s_add_i32 s12, s52, s19
	s_ashr_i32 s13, s12, 31
	s_and_b32 s53, s59, 0x7fff
	s_waitcnt lgkmcnt(0)
	v_readfirstlane_b32 s60, v2
	s_lshl_b64 s[14:15], s[12:13], 2
	v_readfirstlane_b32 s61, v3
	s_add_u32 s60, s60, s14
	s_addc_u32 s61, s61, s15
	v_lshl_or_b32 v0, s53, 14, v131
	v_lshl_add_u64 v[2:3], s[22:23], 0, v[0:1]
	v_lshl_add_u64 v[2:3], v[2:3], 0, s[14:15]
	s_and_b32 s98, 0xffff, s59
	s_lshl_b32 s98, s98, 9
	s_lshl_b32 s99, s24, 7
	s_or_b32 s98, s98, s99
	s_mov_b32 s99, s25
	v_lshl_add_u64 v[184:185], s[98:99], 0, v[76:77]
	v_lshl_add_u64 v[186:187], s[98:99], 0, v[84:85]
	v_lshl_add_u64 v[188:189], s[98:99], 0, v[86:87]
	v_lshl_add_u64 v[190:191], s[98:99], 0, v[88:89]
	v_lshlrev_b64 v[184:185], 8, v[184:185]
	v_lshlrev_b64 v[186:187], 8, v[186:187]
	v_lshlrev_b64 v[188:189], 8, v[188:189]
	v_lshlrev_b64 v[190:191], 8, v[190:191]
	v_lshl_add_u64 v[184:185], v[68:69], 0, v[184:185]
	v_lshl_add_u64 v[186:187], v[68:69], 0, v[186:187]
	v_lshl_add_u64 v[188:189], v[68:69], 0, v[188:189]
	v_lshl_add_u64 v[190:191], v[68:69], 0, v[190:191]
	global_load_dwordx4 v[232:235], v[184:185], off
	global_load_dwordx4 v[236:239], v[186:187], off
	global_load_dwordx4 v[240:243], v[188:189], off
	global_load_dwordx4 v[244:247], v[190:191], off
	global_load_dword v6, v1, s[60:61]
	global_load_dword v5, v[2:3], off offset:128
	global_load_dword v4, v[2:3], off
	v_and_b32_e32 v7, 64, v145
	v_add_u32_e32 v0, -1, v145
	v_cmp_lt_i32_e32 vcc, v0, v7
	s_lshl_b32 s53, s53, 5
	s_waitcnt vmcnt(0)
	v_mov_b32_e32 v3, v4
	v_cndmask_b32_e32 v2, v0, v145, vcc
	v_mul_f32_e32 v0, 0x3fb8aa3b, v6
	v_exp_f32_e32 v0, v0
	v_lshlrev_b32_e32 v6, 2, v2
	v_mov_b32_e32 v2, v5
	v_pk_mul_f32 v[2:3], v[2:3], v[0:1] op_sel_hi:[1,0] neg_lo:[0,1]
	s_nop 0
	v_sub_f32_e32 v0, v2, v3
	ds_bpermute_b32 v3, v6, v0
	v_add_u32_e32 v6, -2, v145
	v_cmp_lt_i32_e32 vcc, v6, v7
	s_waitcnt lgkmcnt(0)
	v_add_f32_e32 v3, v0, v3
	v_cndmask_b32_e32 v6, v6, v145, vcc
	v_lshlrev_b32_e32 v6, 2, v6
	v_cndmask_b32_e64 v0, v3, v0, s[0:1]
	ds_bpermute_b32 v3, v6, v0
	v_add_u32_e32 v6, -4, v145
	v_cmp_lt_i32_e32 vcc, v6, v7
	s_waitcnt lgkmcnt(0)
	v_add_f32_e32 v3, v0, v3
	v_cndmask_b32_e32 v6, v6, v145, vcc
	v_lshlrev_b32_e32 v6, 2, v6
	v_cndmask_b32_e64 v0, v3, v0, s[16:17]
	ds_bpermute_b32 v3, v6, v0
	v_add_u32_e32 v6, -8, v145
	v_cmp_lt_i32_e32 vcc, v6, v7
	s_waitcnt lgkmcnt(0)
	v_add_f32_e32 v3, v0, v3
	v_cndmask_b32_e32 v6, v6, v145, vcc
	v_lshlrev_b32_e32 v6, 2, v6
	v_cndmask_b32_e64 v0, v3, v0, s[4:5]
	ds_bpermute_b32 v3, v6, v0
	v_add_u32_e32 v6, -16, v145
	v_cmp_lt_i32_e32 vcc, v6, v7
	s_waitcnt lgkmcnt(0)
	v_add_f32_e32 v3, v0, v3
	v_cndmask_b32_e32 v6, v6, v145, vcc
	v_lshlrev_b32_e32 v6, 2, v6
	v_cndmask_b32_e64 v0, v3, v0, s[6:7]
	ds_bpermute_b32 v3, v6, v0
	v_subrev_u32_e32 v6, 32, v145
	v_cmp_lt_i32_e32 vcc, v6, v7
	s_waitcnt lgkmcnt(0)
	v_add_f32_e32 v3, v0, v3
	v_cndmask_b32_e32 v6, v6, v145, vcc
	v_lshlrev_b32_e32 v6, 2, v6
	v_cndmask_b32_e64 v0, v3, v0, s[8:9]
	ds_bpermute_b32 v3, v6, v0
	v_add_u32_e32 v6, s55, v121
	s_waitcnt lgkmcnt(0)
	v_add_f32_e32 v3, v0, v3
	v_cndmask_b32_e64 v3, v3, v0, s[10:11]
	ds_bpermute_b32 v0, v146, v3
	v_sub_f32_e32 v2, v3, v2
	s_waitcnt lgkmcnt(0)
	v_sub_f32_e32 v2, v0, v2
	v_sub_f32_e32 v3, v0, v3
	v_mul_f32_e32 v2, 0x3fb8aa3b, v2
	v_mul_f32_e32 v3, 0x3fb8aa3b, v3
	v_exp_f32_e32 v2, v2
	v_exp_f32_e32 v3, v3
	s_nop 0
	v_pk_mul_f32 v[2:3], v[4:5], v[2:3]
	ds_write_b64 v6, v[2:3]
	s_and_saveexec_b64 s[14:15], s[0:1]
	s_cbranch_execz .LBB0_339
	v_mul_f32_e32 v0, 0x3fb8aa3b, v0
	s_add_i32 s12, s53, s12
	v_exp_f32_e32 v0, v0
	s_ashr_i32 s13, s12, 31
	s_lshl_b64 s[12:13], s[12:13], 2
	s_add_u32 s12, s33, s12
	s_addc_u32 s13, s54, s13
	global_store_dword v1, v0, s[12:13]
.LBB0_339:
	s_or_b64 exec, exec, s[14:15]
	s_and_b32 s12, 0xffff, s59
	s_lshl_b32 s13, s12, 9
	s_lshl_b32 s14, s24, 7
	s_or_b32 s24, s13, s14
	v_lshl_add_u64 v[2:3], s[24:25], 0, v[76:77]
	v_lshl_add_u64 v[4:5], s[24:25], 0, v[84:85]
	v_lshl_add_u64 v[10:11], s[24:25], 0, v[86:87]
	v_lshl_add_u64 v[12:13], s[24:25], 0, v[88:89]
	v_lshlrev_b64 v[2:3], 8, v[2:3]
	v_lshlrev_b64 v[4:5], 8, v[4:5]
	v_lshlrev_b64 v[10:11], 8, v[10:11]
	v_lshlrev_b64 v[12:13], 8, v[12:13]
	v_lshl_add_u64 v[2:3], v[68:69], 0, v[2:3]
	v_lshl_add_u64 v[6:7], v[68:69], 0, v[4:5]
	v_lshl_add_u64 v[10:11], v[68:69], 0, v[10:11]
	v_lshl_add_u64 v[14:15], v[68:69], 0, v[12:13]
	s_nop 0
	s_nop 0
	s_nop 0
	v_add_u32_e32 v0, v126, v132
	v_mov_b32_e32 v123, v67
	s_mov_b32 s24, 0
	v_lshl_or_b32 v122, s12, 11, v120
	s_mov_b64 s[12:13], -1
	s_waitcnt vmcnt(3)
	ds_write_b128 v0, v[232:235] offset:4096
	s_waitcnt vmcnt(2)
	ds_write_b128 v136, v[236:239] offset:4096
	s_waitcnt vmcnt(1)
	ds_write_b128 v137, v[240:243] offset:4096
	s_waitcnt vmcnt(0)
	ds_write_b128 v138, v[244:247] offset:4096
	s_waitcnt lgkmcnt(0)
	s_barrier
; #define LAS __attribute__((address_space(3)))
; __device__ __forceinline__ void unpack8(u32x4 r, float* f) { f[0] = bflo(r.x); f[1] = bfhi(r.x); f[2] = bflo(r.y); f[3] = bfhi(r.y); f[4] = bflo(r.z); f[5] = bfhi(r.z); f[6] = bflo(r.w); f[7] = bfhi(r.w); }
; __device__ __forceinline__ u32x4 pack8(const float* f) { u32x4 o; o.x = pk2(f[0], f[1]); o.y = pk2(f[2], f[3]); o.z = pk2(f[4], f[5]); o.w = pk2(f[6], f[7]); return o; }
; __device__ __forceinline__ f32x16 mfma32(bf16x8 a, bf16x8 b, f32x16 c) { return __builtin_amdgcn_mfma_f32_32x32x16_bf16(a, b, c, 0, 0, 0); }
; __device__ __forceinline__ void phase_mix(const PT& p, LAS unsigned char* lds, int tid, int lane, int wave) {
;     ...
;             for (int tk = 0; tk < 2; ++tk) {
;                 const int r = (wave >> 1) + 4 * tk, pb = wave & 1, hh = grp * 8 + r;
;                 const bf16* ap = xT + ((size_t)bc * 2048 + hh * 64 + pb * 32 + r32) * 128 + 8 * h;
;                 const LAS unsigned char* bp = lds + ST_BOFF + r32 * 272 + 16 * h;
;                 f32x16 acc[4];
; #pragma unroll
;                 for (int nb = 0; nb < 4; ++nb)
; #pragma unroll
;                     for (int i = 0; i < 16; ++i) acc[nb][i] = 0.f;
; #pragma unroll
;                 for (int st = 0; st < 8; ++st) {
;                     float f[8]; unpack8(*(const u32x4*)(ap + 16 * st), f);
;                     const f32x4 w0 = *(const LAS f32x4*)(wtab + r * 128 + 16 * st + 8 * h), w1 = *(const LAS f32x4*)(wtab + r * 128 + 16 * st + 8 * h + 4);
;                     f[0] *= w0.x; f[1] *= w0.y; f[2] *= w0.z; f[3] *= w0.w; f[4] *= w1.x; f[5] *= w1.y; f[6] *= w1.z; f[7] *= w1.w;
;                     const bf16x8 a = __builtin_bit_cast(bf16x8, pack8(f));
; #pragma unroll
;                     for (int nb = 0; nb < 4; ++nb) { const bf16x8 bfr = __builtin_bit_cast(bf16x8, *(const LAS u32x4*)(bp + nb * 32 * 272 + 32 * st)); acc[nb] = mfma32(a, bfr, acc[nb]); }
.LBB0_340:
	s_add_i32 s15, s24, s56
	s_add_i32 s14, s15, s52
	s_lshl_b32 s60, s14, 6
	s_ashr_i32 s61, s60, 31
	v_lshl_add_u64 v[2:3], v[122:123], 0, s[60:61]
	v_lshlrev_b64 v[2:3], 8, v[2:3]
	v_lshl_add_u64 v[124:125], v[70:71], 0, v[2:3]
	global_load_dwordx4 v[200:203], v[124:125], off
	global_load_dwordx4 v[204:207], v[124:125], off offset:32
	global_load_dwordx4 v[208:211], v[124:125], off offset:64
	global_load_dwordx4 v[212:215], v[124:125], off offset:96
	global_load_dwordx4 v[216:219], v[124:125], off offset:128
	global_load_dwordx4 v[220:223], v[124:125], off offset:160
	global_load_dwordx4 v[224:227], v[124:125], off offset:192
	global_load_dwordx4 v[228:231], v[124:125], off offset:224
	v_lshl_add_u32 v0, s15, 9, v127
	ds_read_b128 v[6:9], v0
	ds_read_b128 v[10:13], v0 offset:16
	s_waitcnt vmcnt(7)
	v_mov_b32_e32 v2, v200
	v_mov_b32_e32 v3, v201
	v_mov_b32_e32 v4, v202
	v_mov_b32_e32 v5, v203
	v_lshlrev_b32_e32 v14, 16, v2
	v_and_b32_e32 v15, 0xffff0000, v2
	v_lshlrev_b32_e32 v2, 16, v3
	v_and_b32_e32 v3, 0xffff0000, v3
	v_lshlrev_b32_e32 v16, 16, v4
	v_and_b32_e32 v17, 0xffff0000, v4
	v_lshlrev_b32_e32 v4, 16, v5
	v_and_b32_e32 v5, 0xffff0000, v5
	s_waitcnt lgkmcnt(1)
	v_pk_mul_f32 v[6:7], v[6:7], v[14:15]
	v_pk_mul_f32 v[8:9], v[8:9], v[2:3]
	s_waitcnt lgkmcnt(0)
	v_pk_mul_f32 v[10:11], v[10:11], v[16:17]
	v_pk_mul_f32 v[12:13], v[12:13], v[4:5]
	v_cvt_pk_bf16_f32 v2, v6, v7
	v_cvt_pk_bf16_f32 v3, v8, v9
	v_cvt_pk_bf16_f32 v4, v10, v11
	v_cvt_pk_bf16_f32 v5, v12, v13
	ds_read_b128 v[6:9], v139 offset:4096
	ds_read_b128 v[10:13], v139 offset:12800
	s_waitcnt lgkmcnt(1)
	v_mfma_f32_32x32x16_bf16 v[50:65], v[2:5], v[6:9], 0
	s_waitcnt lgkmcnt(0)
	v_mfma_f32_32x32x16_bf16 v[34:49], v[2:5], v[10:13], 0
	ds_read_b128 v[6:9], v139 offset:21504
	ds_read_b128 v[10:13], v139 offset:30208
	s_waitcnt lgkmcnt(1)
	v_mfma_f32_32x32x16_bf16 v[18:33], v[2:5], v[6:9], 0
	s_waitcnt lgkmcnt(0)
	v_mfma_f32_32x32x16_bf16 v[2:17], v[2:5], v[10:13], 0
	ds_read_b128 v[154:157], v0 offset:64
	ds_read_b128 v[158:161], v0 offset:80
	s_waitcnt vmcnt(6)
	v_mov_b32_e32 v150, v204
	v_mov_b32_e32 v151, v205
	v_mov_b32_e32 v152, v206
	v_mov_b32_e32 v153, v207
	v_lshlrev_b32_e32 v162, 16, v150
	v_and_b32_e32 v163, 0xffff0000, v150
	v_lshlrev_b32_e32 v150, 16, v151
	v_and_b32_e32 v151, 0xffff0000, v151
	v_lshlrev_b32_e32 v164, 16, v152
	v_and_b32_e32 v165, 0xffff0000, v152
	v_lshlrev_b32_e32 v152, 16, v153
	v_and_b32_e32 v153, 0xffff0000, v153
	s_waitcnt lgkmcnt(1)
	v_pk_mul_f32 v[154:155], v[154:155], v[162:163]
	v_pk_mul_f32 v[156:157], v[156:157], v[150:151]
	s_waitcnt lgkmcnt(0)
	v_pk_mul_f32 v[158:159], v[158:159], v[164:165]
	v_pk_mul_f32 v[160:161], v[160:161], v[152:153]
	v_cvt_pk_bf16_f32 v150, v154, v155
	v_cvt_pk_bf16_f32 v151, v156, v157
	v_cvt_pk_bf16_f32 v152, v158, v159
	v_cvt_pk_bf16_f32 v153, v160, v161
	ds_read_b128 v[154:157], v139 offset:4128
	ds_read_b128 v[158:161], v139 offset:12832
	s_waitcnt lgkmcnt(1)
	v_mfma_f32_32x32x16_bf16 v[50:65], v[150:153], v[154:157], v[50:65]
	s_waitcnt lgkmcnt(0)
	v_mfma_f32_32x32x16_bf16 v[34:49], v[150:153], v[158:161], v[34:49]
	ds_read_b128 v[154:157], v139 offset:21536
	ds_read_b128 v[158:161], v139 offset:30240
	s_waitcnt lgkmcnt(1)
	v_mfma_f32_32x32x16_bf16 v[18:33], v[150:153], v[154:157], v[18:33]
	s_waitcnt lgkmcnt(0)
	v_mfma_f32_32x32x16_bf16 v[2:17], v[150:153], v[158:161], v[2:17]
	ds_read_b128 v[154:157], v0 offset:128
	ds_read_b128 v[158:161], v0 offset:144
	s_waitcnt vmcnt(5)
	v_mov_b32_e32 v150, v208
	v_mov_b32_e32 v151, v209
	v_mov_b32_e32 v152, v210
	v_mov_b32_e32 v153, v211
	v_lshlrev_b32_e32 v162, 16, v150
	v_and_b32_e32 v163, 0xffff0000, v150
	v_lshlrev_b32_e32 v150, 16, v151
	v_and_b32_e32 v151, 0xffff0000, v151
	v_lshlrev_b32_e32 v164, 16, v152
	v_and_b32_e32 v165, 0xffff0000, v152
	v_lshlrev_b32_e32 v152, 16, v153
	v_and_b32_e32 v153, 0xffff0000, v153
	s_waitcnt lgkmcnt(1)
	v_pk_mul_f32 v[154:155], v[154:155], v[162:163]
	v_pk_mul_f32 v[156:157], v[156:157], v[150:151]
	s_waitcnt lgkmcnt(0)
	v_pk_mul_f32 v[158:159], v[158:159], v[164:165]
	v_pk_mul_f32 v[160:161], v[160:161], v[152:153]
	v_cvt_pk_bf16_f32 v150, v154, v155
	v_cvt_pk_bf16_f32 v151, v156, v157
	v_cvt_pk_bf16_f32 v152, v158, v159
	v_cvt_pk_bf16_f32 v153, v160, v161
	ds_read_b128 v[154:157], v139 offset:4160
	ds_read_b128 v[158:161], v139 offset:12864
	s_waitcnt lgkmcnt(1)
	v_mfma_f32_32x32x16_bf16 v[50:65], v[150:153], v[154:157], v[50:65]
	s_waitcnt lgkmcnt(0)
	v_mfma_f32_32x32x16_bf16 v[34:49], v[150:153], v[158:161], v[34:49]
	ds_read_b128 v[154:157], v139 offset:21568
	ds_read_b128 v[158:161], v139 offset:30272
	s_waitcnt lgkmcnt(1)
	v_mfma_f32_32x32x16_bf16 v[18:33], v[150:153], v[154:157], v[18:33]
	s_waitcnt lgkmcnt(0)
	v_mfma_f32_32x32x16_bf16 v[2:17], v[150:153], v[158:161], v[2:17]
	ds_read_b128 v[154:157], v0 offset:192
	ds_read_b128 v[158:161], v0 offset:208
	s_waitcnt vmcnt(4)
	v_mov_b32_e32 v150, v212
	v_mov_b32_e32 v151, v213
	v_mov_b32_e32 v152, v214
	v_mov_b32_e32 v153, v215
	v_lshlrev_b32_e32 v162, 16, v150
	v_and_b32_e32 v163, 0xffff0000, v150
	v_lshlrev_b32_e32 v150, 16, v151
	v_and_b32_e32 v151, 0xffff0000, v151
	v_lshlrev_b32_e32 v164, 16, v152
	v_and_b32_e32 v165, 0xffff0000, v152
	v_lshlrev_b32_e32 v152, 16, v153
	v_and_b32_e32 v153, 0xffff0000, v153
	s_waitcnt lgkmcnt(1)
	v_pk_mul_f32 v[154:155], v[154:155], v[162:163]
	v_pk_mul_f32 v[156:157], v[156:157], v[150:151]
	s_waitcnt lgkmcnt(0)
	v_pk_mul_f32 v[158:159], v[158:159], v[164:165]
	v_pk_mul_f32 v[160:161], v[160:161], v[152:153]
	v_cvt_pk_bf16_f32 v150, v154, v155
	v_cvt_pk_bf16_f32 v151, v156, v157
	v_cvt_pk_bf16_f32 v152, v158, v159
	v_cvt_pk_bf16_f32 v153, v160, v161
	ds_read_b128 v[154:157], v139 offset:4192
	ds_read_b128 v[158:161], v139 offset:12896
	s_waitcnt lgkmcnt(1)
; #define LAS __attribute__((address_space(3)))
; __device__ __forceinline__ void unpack8(u32x4 r, float* f) { f[0] = bflo(r.x); f[1] = bfhi(r.x); f[2] = bflo(r.y); f[3] = bfhi(r.y); f[4] = bflo(r.z); f[5] = bfhi(r.z); f[6] = bflo(r.w); f[7] = bfhi(r.w); }
; __device__ __forceinline__ u32x4 pack8(const float* f) { u32x4 o; o.x = pk2(f[0], f[1]); o.y = pk2(f[2], f[3]); o.z = pk2(f[4], f[5]); o.w = pk2(f[6], f[7]); return o; }
; __device__ __forceinline__ f32x16 mfma32(bf16x8 a, bf16x8 b, f32x16 c) { return __builtin_amdgcn_mfma_f32_32x32x16_bf16(a, b, c, 0, 0, 0); }
; __device__ __forceinline__ void phase_mix(const PT& p, LAS unsigned char* lds, int tid, int lane, int wave) {
;     ...
;                 for (int st = 0; st < 8; ++st) {
;                     float f[8]; unpack8(*(const u32x4*)(ap + 16 * st), f);
;                     const f32x4 w0 = *(const LAS f32x4*)(wtab + r * 128 + 16 * st + 8 * h), w1 = *(const LAS f32x4*)(wtab + r * 128 + 16 * st + 8 * h + 4);
;                     f[0] *= w0.x; f[1] *= w0.y; f[2] *= w0.z; f[3] *= w0.w; f[4] *= w1.x; f[5] *= w1.y; f[6] *= w1.z; f[7] *= w1.w;
;                     const bf16x8 a = __builtin_bit_cast(bf16x8, pack8(f));
; #pragma unroll
;                     for (int nb = 0; nb < 4; ++nb) { const bf16x8 bfr = __builtin_bit_cast(bf16x8, *(const LAS u32x4*)(bp + nb * 32 * 272 + 32 * st)); acc[nb] = mfma32(a, bfr, acc[nb]); }
	v_mfma_f32_32x32x16_bf16 v[50:65], v[150:153], v[154:157], v[50:65]
	s_waitcnt lgkmcnt(0)
	v_mfma_f32_32x32x16_bf16 v[34:49], v[150:153], v[158:161], v[34:49]
	ds_read_b128 v[154:157], v139 offset:21600
	ds_read_b128 v[158:161], v139 offset:30304
	s_waitcnt lgkmcnt(1)
	v_mfma_f32_32x32x16_bf16 v[18:33], v[150:153], v[154:157], v[18:33]
	s_waitcnt lgkmcnt(0)
	v_mfma_f32_32x32x16_bf16 v[2:17], v[150:153], v[158:161], v[2:17]
	ds_read_b128 v[154:157], v0 offset:256
	ds_read_b128 v[158:161], v0 offset:272
	s_waitcnt vmcnt(3)
	v_mov_b32_e32 v150, v216
	v_mov_b32_e32 v151, v217
	v_mov_b32_e32 v152, v218
	v_mov_b32_e32 v153, v219
	v_lshlrev_b32_e32 v162, 16, v150
	v_and_b32_e32 v163, 0xffff0000, v150
	v_lshlrev_b32_e32 v150, 16, v151
	v_and_b32_e32 v151, 0xffff0000, v151
	v_lshlrev_b32_e32 v164, 16, v152
	v_and_b32_e32 v165, 0xffff0000, v152
	v_lshlrev_b32_e32 v152, 16, v153
	v_and_b32_e32 v153, 0xffff0000, v153
	s_waitcnt lgkmcnt(1)
	v_pk_mul_f32 v[154:155], v[154:155], v[162:163]
	v_pk_mul_f32 v[156:157], v[156:157], v[150:151]
	s_waitcnt lgkmcnt(0)
	v_pk_mul_f32 v[158:159], v[158:159], v[164:165]
	v_pk_mul_f32 v[160:161], v[160:161], v[152:153]
	v_cvt_pk_bf16_f32 v150, v154, v155
	v_cvt_pk_bf16_f32 v151, v156, v157
	v_cvt_pk_bf16_f32 v152, v158, v159
	v_cvt_pk_bf16_f32 v153, v160, v161
	ds_read_b128 v[154:157], v139 offset:4224
	ds_read_b128 v[158:161], v139 offset:12928
	s_waitcnt lgkmcnt(1)
	v_mfma_f32_32x32x16_bf16 v[50:65], v[150:153], v[154:157], v[50:65]
	s_waitcnt lgkmcnt(0)
	v_mfma_f32_32x32x16_bf16 v[34:49], v[150:153], v[158:161], v[34:49]
	ds_read_b128 v[154:157], v139 offset:21632
	ds_read_b128 v[158:161], v139 offset:30336
	s_waitcnt lgkmcnt(1)
	v_mfma_f32_32x32x16_bf16 v[18:33], v[150:153], v[154:157], v[18:33]
	s_waitcnt lgkmcnt(0)
	v_mfma_f32_32x32x16_bf16 v[2:17], v[150:153], v[158:161], v[2:17]
	ds_read_b128 v[154:157], v0 offset:320
	ds_read_b128 v[158:161], v0 offset:336
	s_waitcnt vmcnt(2)
	v_mov_b32_e32 v150, v220
	v_mov_b32_e32 v151, v221
	v_mov_b32_e32 v152, v222
	v_mov_b32_e32 v153, v223
	v_lshlrev_b32_e32 v162, 16, v150
	v_and_b32_e32 v163, 0xffff0000, v150
	v_lshlrev_b32_e32 v150, 16, v151
	v_and_b32_e32 v151, 0xffff0000, v151
	v_lshlrev_b32_e32 v164, 16, v152
	v_and_b32_e32 v165, 0xffff0000, v152
	v_lshlrev_b32_e32 v152, 16, v153
	v_and_b32_e32 v153, 0xffff0000, v153
	s_waitcnt lgkmcnt(1)
	v_pk_mul_f32 v[154:155], v[154:155], v[162:163]
	v_pk_mul_f32 v[156:157], v[156:157], v[150:151]
	s_waitcnt lgkmcnt(0)
	v_pk_mul_f32 v[158:159], v[158:159], v[164:165]
	v_pk_mul_f32 v[160:161], v[160:161], v[152:153]
	v_cvt_pk_bf16_f32 v150, v154, v155
	v_cvt_pk_bf16_f32 v151, v156, v157
	v_cvt_pk_bf16_f32 v152, v158, v159
	v_cvt_pk_bf16_f32 v153, v160, v161
	ds_read_b128 v[154:157], v139 offset:4256
	ds_read_b128 v[158:161], v139 offset:12960
	s_waitcnt lgkmcnt(1)
	v_mfma_f32_32x32x16_bf16 v[50:65], v[150:153], v[154:157], v[50:65]
	s_waitcnt lgkmcnt(0)
	v_mfma_f32_32x32x16_bf16 v[34:49], v[150:153], v[158:161], v[34:49]
	ds_read_b128 v[154:157], v139 offset:21664
	ds_read_b128 v[158:161], v139 offset:30368
	s_waitcnt lgkmcnt(1)
	v_mfma_f32_32x32x16_bf16 v[18:33], v[150:153], v[154:157], v[18:33]
	s_waitcnt lgkmcnt(0)
	v_mfma_f32_32x32x16_bf16 v[2:17], v[150:153], v[158:161], v[2:17]
	ds_read_b128 v[154:157], v0 offset:384
	ds_read_b128 v[158:161], v0 offset:400
	s_waitcnt vmcnt(1)
	v_mov_b32_e32 v150, v224
	v_mov_b32_e32 v151, v225
	v_mov_b32_e32 v152, v226
	v_mov_b32_e32 v153, v227
	v_lshlrev_b32_e32 v162, 16, v150
	v_and_b32_e32 v163, 0xffff0000, v150
	v_lshlrev_b32_e32 v150, 16, v151
	v_and_b32_e32 v151, 0xffff0000, v151
	v_lshlrev_b32_e32 v164, 16, v152
	v_and_b32_e32 v165, 0xffff0000, v152
	v_lshlrev_b32_e32 v152, 16, v153
	v_and_b32_e32 v153, 0xffff0000, v153
	s_waitcnt lgkmcnt(1)
	v_pk_mul_f32 v[154:155], v[154:155], v[162:163]
	v_pk_mul_f32 v[156:157], v[156:157], v[150:151]
	s_waitcnt lgkmcnt(0)
	v_pk_mul_f32 v[158:159], v[158:159], v[164:165]
	v_pk_mul_f32 v[160:161], v[160:161], v[152:153]
	v_cvt_pk_bf16_f32 v150, v154, v155
	v_cvt_pk_bf16_f32 v151, v156, v157
	v_cvt_pk_bf16_f32 v152, v158, v159
	v_cvt_pk_bf16_f32 v153, v160, v161
	ds_read_b128 v[154:157], v139 offset:4288
	ds_read_b128 v[158:161], v139 offset:12992
	s_waitcnt lgkmcnt(1)
	v_mfma_f32_32x32x16_bf16 v[50:65], v[150:153], v[154:157], v[50:65]
	s_waitcnt lgkmcnt(0)
	v_mfma_f32_32x32x16_bf16 v[34:49], v[150:153], v[158:161], v[34:49]
	ds_read_b128 v[154:157], v139 offset:21696
	ds_read_b128 v[158:161], v139 offset:30400
	s_waitcnt lgkmcnt(1)
	v_mfma_f32_32x32x16_bf16 v[18:33], v[150:153], v[154:157], v[18:33]
	s_waitcnt lgkmcnt(0)
	v_mfma_f32_32x32x16_bf16 v[2:17], v[150:153], v[158:161], v[2:17]
	ds_read_b128 v[154:157], v0 offset:448
	ds_read_b128 v[158:161], v0 offset:464
	s_waitcnt vmcnt(0)
	v_mov_b32_e32 v150, v228
	v_mov_b32_e32 v151, v229
	v_mov_b32_e32 v152, v230
	v_mov_b32_e32 v153, v231
	v_lshlrev_b32_e32 v124, 16, v150
	v_and_b32_e32 v125, 0xffff0000, v150
	v_lshlrev_b32_e32 v150, 16, v151
	v_and_b32_e32 v151, 0xffff0000, v151
	v_lshlrev_b32_e32 v162, 16, v152
	v_and_b32_e32 v163, 0xffff0000, v152
	v_lshlrev_b32_e32 v152, 16, v153
	v_and_b32_e32 v153, 0xffff0000, v153
	s_waitcnt lgkmcnt(1)
	v_pk_mul_f32 v[124:125], v[154:155], v[124:125]
	v_pk_mul_f32 v[154:155], v[156:157], v[150:151]
	s_waitcnt lgkmcnt(0)
	v_pk_mul_f32 v[156:157], v[158:159], v[162:163]
	v_pk_mul_f32 v[158:159], v[160:161], v[152:153]
	v_cvt_pk_bf16_f32 v150, v124, v125
	v_cvt_pk_bf16_f32 v151, v154, v155
	v_cvt_pk_bf16_f32 v152, v156, v157
	v_cvt_pk_bf16_f32 v153, v158, v159
	ds_read_b128 v[154:157], v139 offset:4320
	ds_read_b128 v[158:161], v139 offset:13024
	s_waitcnt lgkmcnt(1)
; #define LAS __attribute__((address_space(3)))
; __device__ __forceinline__ void unpack8(u32x4 r, float* f) { f[0] = bflo(r.x); f[1] = bfhi(r.x); f[2] = bflo(r.y); f[3] = bfhi(r.y); f[4] = bflo(r.z); f[5] = bfhi(r.z); f[6] = bflo(r.w); f[7] = bfhi(r.w); }
; __device__ __forceinline__ u32x4 pack8(const float* f) { u32x4 o; o.x = pk2(f[0], f[1]); o.y = pk2(f[2], f[3]); o.z = pk2(f[4], f[5]); o.w = pk2(f[6], f[7]); return o; }
; __device__ __forceinline__ f32x16 mfma32(bf16x8 a, bf16x8 b, f32x16 c) { return __builtin_amdgcn_mfma_f32_32x32x16_bf16(a, b, c, 0, 0, 0); }
; __device__ __forceinline__ void phase_mix(const PT& p, LAS unsigned char* lds, int tid, int lane, int wave) {
;     ...
;                 for (int st = 0; st < 8; ++st) {
;                     float f[8]; unpack8(*(const u32x4*)(ap + 16 * st), f);
;                     const f32x4 w0 = *(const LAS f32x4*)(wtab + r * 128 + 16 * st + 8 * h), w1 = *(const LAS f32x4*)(wtab + r * 128 + 16 * st + 8 * h + 4);
;                     f[0] *= w0.x; f[1] *= w0.y; f[2] *= w0.z; f[3] *= w0.w; f[4] *= w1.x; f[5] *= w1.y; f[6] *= w1.z; f[7] *= w1.w;
;                     const bf16x8 a = __builtin_bit_cast(bf16x8, pack8(f));
; #pragma unroll
;                     for (int nb = 0; nb < 4; ++nb) { const bf16x8 bfr = __builtin_bit_cast(bf16x8, *(const LAS u32x4*)(bp + nb * 32 * 272 + 32 * st)); acc[nb] = mfma32(a, bfr, acc[nb]); }
	v_mfma_f32_32x32x16_bf16 v[50:65], v[150:153], v[154:157], v[50:65]
	s_waitcnt lgkmcnt(0)
	v_mfma_f32_32x32x16_bf16 v[34:49], v[150:153], v[158:161], v[34:49]
	ds_read_b128 v[154:157], v139 offset:21728
	ds_read_b128 v[158:161], v139 offset:30432
	s_waitcnt lgkmcnt(1)
	v_mfma_f32_32x32x16_bf16 v[18:33], v[150:153], v[154:157], v[18:33]
	s_waitcnt lgkmcnt(0)
; __device__ __forceinline__ int crow(int r, int h) { return (r & 3) + 8 * (r >> 2) + 4 * h; }
; __device__ __forceinline__ void phase_mix(const PT& p, LAS unsigned char* lds, int tid, int lane, int wave) {
;     ...
;                 bf16* sp = ST + ((size_t)(bc * 32 + hh) * 64 + pb * 32) * 128;
; #pragma unroll
;                 for (int nb = 0; nb < 4; ++nb)
; #pragma unroll
;                     for (int i = 0; i < 16; ++i) sp[(size_t)crow(i, h) * 128 + nb * 32 + r32] = (bf16)(pk2(acc[nb][i], 0.f) & 0xffffu);
	v_mfma_f32_32x32x16_bf16 v[2:17], v[150:153], v[158:161], v[2:17]
	s_add_i32 s14, s14, s53
	s_ashr_i32 s15, s14, 31
	s_lshl_b64 s[14:15], s[14:15], 14
	s_nop 8
	v_cvt_pk_bf16_f32 v162, v2, s0
	v_cvt_pk_bf16_f32 v163, v3, s0
	v_lshl_add_u64 v[2:3], v[74:75], 0, s[14:15]
	v_cvt_pk_bf16_f32 v0, v50, s0
	v_cvt_pk_bf16_f32 v150, v46, s0
	v_cvt_pk_bf16_f32 v151, v47, s0
	v_cvt_pk_bf16_f32 v46, v22, s0
	v_cvt_pk_bf16_f32 v47, v23, s0
	v_cvt_pk_bf16_f32 v164, v4, s0
	v_cvt_pk_bf16_f32 v165, v5, s0
	v_cvt_pk_bf16_f32 v166, v6, s0
	v_cvt_pk_bf16_f32 v167, v7, s0
	v_lshl_add_u64 v[4:5], v[2:3], 0, v[72:73]
	v_lshl_add_u64 v[6:7], v[2:3], 0, v[90:91]
	v_lshl_add_u64 v[22:23], v[2:3], 0, 64
	v_cvt_pk_bf16_f32 v50, v51, s0
	v_cvt_pk_bf16_f32 v51, v52, s0
	v_cvt_pk_bf16_f32 v52, v53, s0
	v_cvt_pk_bf16_f32 v53, v54, s0
	v_cvt_pk_bf16_f32 v54, v55, s0
	v_cvt_pk_bf16_f32 v55, v56, s0
	v_cvt_pk_bf16_f32 v56, v57, s0
	v_cvt_pk_bf16_f32 v57, v58, s0
	v_cvt_pk_bf16_f32 v58, v59, s0
	v_cvt_pk_bf16_f32 v59, v60, s0
	v_cvt_pk_bf16_f32 v60, v61, s0
	v_cvt_pk_bf16_f32 v61, v62, s0
	v_cvt_pk_bf16_f32 v62, v63, s0
	v_cvt_pk_bf16_f32 v63, v64, s0
	v_cvt_pk_bf16_f32 v64, v65, s0
	v_cvt_pk_bf16_f32 v34, v34, s0
	v_cvt_pk_bf16_f32 v35, v35, s0
	v_cvt_pk_bf16_f32 v36, v36, s0
	v_cvt_pk_bf16_f32 v37, v37, s0
	v_cvt_pk_bf16_f32 v38, v38, s0
	v_cvt_pk_bf16_f32 v39, v39, s0
	v_cvt_pk_bf16_f32 v40, v40, s0
	v_cvt_pk_bf16_f32 v41, v41, s0
	v_cvt_pk_bf16_f32 v65, v42, s0
	v_cvt_pk_bf16_f32 v124, v43, s0
	v_cvt_pk_bf16_f32 v125, v44, s0
	v_cvt_pk_bf16_f32 v149, v45, s0
	v_cvt_pk_bf16_f32 v152, v48, s0
	v_cvt_pk_bf16_f32 v153, v49, s0
	v_cvt_pk_bf16_f32 v42, v18, s0
	v_cvt_pk_bf16_f32 v43, v19, s0
	v_cvt_pk_bf16_f32 v44, v20, s0
	v_cvt_pk_bf16_f32 v45, v21, s0
	v_cvt_pk_bf16_f32 v48, v24, s0
	v_cvt_pk_bf16_f32 v49, v25, s0
	v_cvt_pk_bf16_f32 v168, v8, s0
	v_cvt_pk_bf16_f32 v169, v9, s0
	v_cvt_pk_bf16_f32 v170, v10, s0
	v_cvt_pk_bf16_f32 v171, v11, s0
	v_cvt_pk_bf16_f32 v172, v12, s0
	v_cvt_pk_bf16_f32 v173, v13, s0
	v_cvt_pk_bf16_f32 v174, v14, s0
	v_cvt_pk_bf16_f32 v175, v15, s0
	v_cvt_pk_bf16_f32 v176, v16, s0
	v_cvt_pk_bf16_f32 v177, v17, s0
	s_mov_b32 s24, 4
	s_and_b64 vcc, exec, s[12:13]
	s_mov_b64 s[12:13], 0
	v_lshl_add_u64 v[8:9], v[2:3], 0, v[92:93]
	v_lshl_add_u64 v[10:11], v[2:3], 0, v[94:95]
	v_lshl_add_u64 v[12:13], v[2:3], 0, v[96:97]
	v_lshl_add_u64 v[14:15], v[2:3], 0, v[98:99]
	v_lshl_add_u64 v[16:17], v[2:3], 0, v[100:101]
	v_lshl_add_u64 v[18:19], v[2:3], 0, v[102:103]
	v_lshl_add_u64 v[20:21], v[2:3], 0, v[104:105]
	v_lshl_add_u64 v[24:25], v[2:3], 0, s[46:47]
	v_lshl_add_u64 v[2:3], v[2:3], 0, s[48:49]
	global_store_short v[4:5], v0, off
	global_store_short v[4:5], v50, off offset:256
	global_store_short v[4:5], v51, off offset:512
	global_store_short v[4:5], v52, off offset:768
	global_store_short v[4:5], v53, off offset:2048
	global_store_short v[4:5], v54, off offset:2304
	global_store_short v[4:5], v55, off offset:2560
	global_store_short v[4:5], v56, off offset:2816
	global_store_short v[6:7], v57, off
	global_store_short v[8:9], v58, off
	global_store_short v[10:11], v59, off
	global_store_short v[12:13], v60, off
	global_store_short v[14:15], v61, off
	global_store_short v[16:17], v62, off
	global_store_short v[18:19], v63, off
	global_store_short v[20:21], v64, off
	global_store_short v[4:5], v34, off offset:64
	global_store_short v[4:5], v35, off offset:320
	global_store_short v[4:5], v36, off offset:576
	global_store_short v[4:5], v37, off offset:832
	global_store_short v[4:5], v38, off offset:2112
	global_store_short v[4:5], v39, off offset:2368
	global_store_short v[4:5], v40, off offset:2624
	global_store_short v[4:5], v41, off offset:2880
	v_lshl_add_u64 v[6:7], v[22:23], 0, v[90:91]
	v_cvt_pk_bf16_f32 v154, v26, s0
	v_cvt_pk_bf16_f32 v155, v27, s0
	v_cvt_pk_bf16_f32 v156, v28, s0
	v_cvt_pk_bf16_f32 v157, v29, s0
	v_cvt_pk_bf16_f32 v158, v30, s0
	v_cvt_pk_bf16_f32 v159, v31, s0
	v_cvt_pk_bf16_f32 v160, v32, s0
	v_cvt_pk_bf16_f32 v161, v33, s0
	v_lshl_add_u64 v[8:9], v[22:23], 0, v[92:93]
	v_lshl_add_u64 v[10:11], v[22:23], 0, v[94:95]
	v_lshl_add_u64 v[12:13], v[22:23], 0, v[96:97]
	v_lshl_add_u64 v[14:15], v[22:23], 0, v[98:99]
	v_lshl_add_u64 v[16:17], v[22:23], 0, v[100:101]
	v_lshl_add_u64 v[18:19], v[22:23], 0, v[102:103]
	v_lshl_add_u64 v[20:21], v[22:23], 0, v[104:105]
	global_store_short v[4:5], v42, off offset:128
	global_store_short v[4:5], v43, off offset:384
	global_store_short v[4:5], v44, off offset:640
	global_store_short v[4:5], v45, off offset:896
	global_store_short v[4:5], v46, off offset:2176
	global_store_short v[4:5], v47, off offset:2432
	global_store_short v[4:5], v48, off offset:2688
	global_store_short v[4:5], v49, off offset:2944
	v_lshl_add_u64 v[22:23], v[24:25], 0, v[90:91]
	v_lshl_add_u64 v[26:27], v[24:25], 0, v[92:93]
	v_lshl_add_u64 v[28:29], v[24:25], 0, v[94:95]
	v_lshl_add_u64 v[30:31], v[24:25], 0, v[96:97]
	v_lshl_add_u64 v[32:33], v[24:25], 0, v[98:99]
	v_lshl_add_u64 v[34:35], v[24:25], 0, v[100:101]
	v_lshl_add_u64 v[36:37], v[24:25], 0, v[102:103]
	v_lshl_add_u64 v[24:25], v[24:25], 0, v[104:105]
	global_store_short v[4:5], v162, off offset:192
	global_store_short v[4:5], v163, off offset:448
	global_store_short v[4:5], v164, off offset:704
	global_store_short v[4:5], v165, off offset:960
	global_store_short v[4:5], v166, off offset:2240
	global_store_short v[4:5], v167, off offset:2496
	global_store_short v[4:5], v168, off offset:2752
	global_store_short v[4:5], v169, off offset:3008
	v_lshl_add_u64 v[4:5], v[2:3], 0, v[90:91]
	v_lshl_add_u64 v[38:39], v[2:3], 0, v[92:93]
	v_lshl_add_u64 v[40:41], v[2:3], 0, v[94:95]
	v_lshl_add_u64 v[42:43], v[2:3], 0, v[96:97]
	v_lshl_add_u64 v[44:45], v[2:3], 0, v[98:99]
	v_lshl_add_u64 v[46:47], v[2:3], 0, v[100:101]
	v_lshl_add_u64 v[48:49], v[2:3], 0, v[102:103]
	v_lshl_add_u64 v[2:3], v[2:3], 0, v[104:105]
	global_store_short v[6:7], v65, off
	global_store_short v[8:9], v124, off
	global_store_short v[10:11], v125, off
	global_store_short v[12:13], v149, off
	global_store_short v[14:15], v150, off
	global_store_short v[16:17], v151, off
	global_store_short v[18:19], v152, off
	global_store_short v[20:21], v153, off
	global_store_short v[22:23], v154, off
	global_store_short v[26:27], v155, off
	global_store_short v[28:29], v156, off
	global_store_short v[30:31], v157, off
	global_store_short v[32:33], v158, off
	global_store_short v[34:35], v159, off
	global_store_short v[36:37], v160, off
	global_store_short v[24:25], v161, off
	global_store_short v[4:5], v170, off
	global_store_short v[38:39], v171, off
	global_store_short v[40:41], v172, off
	global_store_short v[42:43], v173, off
	global_store_short v[44:45], v174, off
	global_store_short v[46:47], v175, off
	global_store_short v[48:49], v176, off
	global_store_short v[2:3], v177, off
	s_cbranch_vccnz .LBB0_340

; __device__ __forceinline__ void chunk_cumsum(const float* DT, const float* a_log, int tok0, int hh, int lane, float& d0, float& d1, float& c0, float& c1, float& tot) {
;     d0 = DT[(size_t)(tok0 + 2 * lane) * 32 + hh]; d1 = DT[(size_t)(tok0 + 2 * lane + 1) * 32 + hh];
;     const float A = -__expf(a_log[hh]); const float x0 = d0 * A, x1 = d1 * A; float ps = x0 + x1;
; #pragma unroll
;     for (int o = 1; o < 64; o <<= 1) { const float t = __shfl_up(ps, o); if (lane >= o) ps += t; }
;     c1 = ps; c0 = ps - x1; tot = __shfl(ps, 63);
; __device__ __forceinline__ void phase_ssd_y(const PT& p, LAS unsigned char* lds, int tid, int lane, int wave) {
;     ...
;         const int bc = it >> 2, grp = it & 3, tok0 = bc * 128;
;         __syncthreads();
;         { const int hh = grp * 8 + wave; float d0, d1, c0, c1, tot; chunk_cumsum(DT, p.in[10], tok0, hh, lane, d0, d1, c0, c1, tot);
;           acum[wave * 128 + 2 * lane] = c0; acum[wave * 128 + 2 * lane + 1] = c1; dtt[wave * 128 + 2 * lane] = d0; dtt[wave * 128 + 2 * lane + 1] = d1; }
.LBB0_484:
	s_barrier
	ds_read_b64 v[0:1], v187
	s_ashr_i32 s2, s84, 2
	s_and_b32 s3, s84, 3
	s_lshl_b32 s92, s2, 7
	s_lshl_b32 s1, s3, 3
	v_readlane_b32 s80, v249, 30
	s_waitcnt lgkmcnt(0)
	v_readfirstlane_b32 s82, v0
	v_or_b32_e32 v0, s92, v119
	s_add_i32 s80, s1, s80
	v_readfirstlane_b32 s1, v1
	v_ashrrev_i32_e32 v1, 31, v0
	v_lshlrev_b64 v[2:3], 7, v[0:1]
	v_or_b32_e32 v0, 1, v0
	v_writelane_b32 v246, s84, 28
	v_readlane_b32 s84, v249, 18
	v_ashrrev_i32_e32 v1, 31, v0
	s_ashr_i32 s81, s80, 31
	v_readlane_b32 s85, v249, 19
	v_lshlrev_b64 v[0:1], 7, v[0:1]
	s_lshl_b64 s[80:81], s[80:81], 2
	v_lshl_add_u64 v[2:3], s[84:85], 0, v[2:3]
	v_lshl_add_u64 v[0:1], s[84:85], 0, v[0:1]
	v_lshl_add_u64 v[2:3], v[2:3], 0, s[80:81]
	v_lshl_add_u64 v[0:1], v[0:1], 0, s[80:81]
	s_add_u32 s80, s82, s80
	s_addc_u32 s81, s1, s81
	global_load_dword v2, v[2:3], off
	s_ashr_i32 s93, s92, 31
	global_load_dword v3, v[0:1], off
	s_lshl_b32 s1, s3, 9
	global_load_dword v0, v121, s[80:81]
	v_readlane_b32 s80, v249, 20
	v_readlane_b32 s81, v249, 21
	s_waitcnt vmcnt(0)
	v_mul_f32_e32 v0, 0x3fb8aa3b, v0
	v_exp_f32_e32 v0, v0
	s_nop 0
	v_mul_f32_e32 v1, v2, v0
	v_fma_f32 v1, v3, -v0, -v1
	ds_bpermute_b32 v4, v123, v1
	s_waitcnt lgkmcnt(0)
	v_add_f32_e32 v4, v1, v4
	v_cndmask_b32_e64 v1, v4, v1, s[80:81]
	ds_bpermute_b32 v4, v125, v1
	v_readlane_b32 s80, v249, 22
	v_readlane_b32 s81, v249, 23
	s_waitcnt lgkmcnt(0)
	v_add_f32_e32 v4, v1, v4
	v_cndmask_b32_e64 v1, v4, v1, s[80:81]
	ds_bpermute_b32 v4, v131, v1
	v_readlane_b32 s80, v249, 24
	v_readlane_b32 s81, v249, 25
	s_waitcnt lgkmcnt(0)
	v_add_f32_e32 v4, v1, v4
	v_cndmask_b32_e64 v1, v4, v1, s[80:81]
	ds_bpermute_b32 v4, v133, v1
	v_readlane_b32 s80, v249, 26
	v_readlane_b32 s81, v249, 27
	s_waitcnt lgkmcnt(0)
	v_add_f32_e32 v4, v1, v4
	v_cndmask_b32_e64 v1, v4, v1, s[80:81]
	ds_bpermute_b32 v4, v135, v1
	v_readlane_b32 s80, v249, 28
	v_readlane_b32 s81, v249, 29
	s_waitcnt lgkmcnt(0)
	v_add_f32_e32 v4, v1, v4
	v_cndmask_b32_e64 v1, v4, v1, s[80:81]
	ds_bpermute_b32 v4, v166, v1
	s_mov_b32 s80, s97
	s_waitcnt lgkmcnt(0)
	v_add_f32_e32 v4, v1, v4
	v_cndmask_b32_e64 v1, v4, v1, s[94:95]
	v_fma_f32 v0, v3, v0, v1
	v_log_f32_e32 v4, v2
	s_nop 0
	v_fmamk_f32 v2, v0, 0xbfb8aa3b, v4
	v_log_f32_e32 v4, v3
	s_nop 0
	v_fmamk_f32 v3, v1, 0xbfb8aa3b, v4
	ds_write2st64_b64 v167, v[0:1], v[2:3] offset1:8

; __device__ __forceinline__ f32x16 mfma32(bf16x8 a, bf16x8 b, f32x16 c) { return __builtin_amdgcn_mfma_f32_32x32x16_bf16(a, b, c, 0, 0, 0); }
; __device__ __forceinline__ void phase_ssd_y(const PT& p, LAS unsigned char* lds, int tid, int lane, int wave) {
;     ...
;         for (int r = 0; r < 8; ++r) {
;             const int hh = grp * 8 + r;
;             f32x16 acc;
; #pragma unroll
;             for (int i = 0; i < 16; ++i) acc[i] = 0.f;
;             const bf16* pp = PV + ((size_t)(bc * 32 + hh) * 64 + pb * 32 + r32) * 128 + 8 * h;
; #pragma unroll
;             for (int st = 0; st < 8; ++st) acc = mfma32(ld_frag16(pp + 16 * st), cf[st], acc);
;             const float al = acum[r * 128 + l]; const float el = __expf(al); const float dsk = p.in[11][hh];
; #pragma unroll
;             for (int i = 0; i < 16; ++i) acc[i] *= el;
.LBB0_493:
	v_readlane_b32 s3, v246, 25
	s_and_b32 s3, s3, 3
	s_lshl_b32 s84, s3, 3
	s_lshl_b32 s85, s2, 5
	s_lshl_b32 s96, s3, 5
	s_lshl_b32 s94, s3, 17
	s_ashr_i32 s3, s2, 31
	s_or_b32 s84, s85, s84
	s_ashr_i32 s85, s84, 31
	s_lshl_b64 s[2:3], s[2:3], 19
	s_lshl_b64 s[84:85], s[84:85], 14
	s_or_b32 s2, s2, s94
	v_lshl_add_u64 v[142:143], v[136:137], 0, s[84:85]
	v_lshl_add_u64 v[144:145], v[138:139], 0, s[2:3]
	v_mov_b32_e32 v210, 0
	s_mov_b64 s[94:95], 0
	s_mov_b64 s[2:3], s[96:97]
	s_branch .LBB0_495
.LBB0_495:
	v_readfirstlane_b32 s98, v117
	v_bfe_u32 v164, v117, 5, 1
	s_nop 3
	s_bfe_u32 s98, s98, 0x20006
	v_bfe_u32 v165, v117, 8, 1
	v_mov_b32_e32 v163, 0xbfb8aa3b
	v_lshlrev_b32_e32 v244, 2, v164
	v_sub_u32_e32 v160, v116, v244
	v_lshlrev_b32_e32 v161, 4, v164
	v_lshlrev_b32_e32 v141, 2, v124
	v_mul_u32_u24_e32 v162, 0x410, v124
	v_lshlrev_b32_e32 v245, 6, v165
	v_lshlrev_b32_e32 v244, 3, v164
	v_add3_u32 v162, v162, v245, v244
	v_add_u32_e32 v162, 0x2600, v162
	ds_read_b64 v[112:113], v188
	v_mov_b32_e32 v126, v210
	s_waitcnt lgkmcnt(0)
	v_readfirstlane_b32 s84, v112
	v_readfirstlane_b32 s85, v113
	s_nop 3
	s_add_u32 s84, s84, s2
	s_addc_u32 s85, s85, s3
	s_cmp_eq_u32 s98, 0
	s_cbranch_scc1 .Lp5v0
	s_cmp_eq_u32 s98, 1
	s_cbranch_scc1 .Lp5v1
	s_cmp_eq_u32 s98, 2
	s_cbranch_scc1 .Lp5v2
	s_branch .Lp5v3
.Lp5v3:
	v_lshl_add_u64 v[212:213], v[142:143], 0, s[94:95]
	v_lshl_add_u64 v[206:207], v[144:145], 0, s[94:95]
	v_mov_b32_e32 v164, 0
	v_add_co_u32_e32 v206, vcc, 0x1a900000, v206
	s_nop 1
	v_addc_co_u32_e32 v207, vcc, 0, v207, vcc
	v_add_co_u32_e32 v184, vcc, 0x4000, v206
	s_nop 1
	v_addc_co_u32_e32 v185, vcc, 0, v207, vcc
	global_load_dword v159, v164, s[84:85]
	global_load_dwordx4 v[170:173], v[212:213], off
	global_load_dwordx4 v[174:177], v[212:213], off offset:32
	global_load_dwordx4 v[178:181], v[212:213], off offset:64
	global_load_dwordx4 v[220:223], v[212:213], off offset:96
	global_load_dwordx4 v[224:227], v[212:213], off offset:128
	global_load_dwordx4 v[228:231], v[212:213], off offset:160
	global_load_dwordx4 v[232:235], v[212:213], off offset:192
	global_load_dwordx4 v[208:211], v[212:213], off offset:224
	global_load_dwordx2 v[150:151], v[206:207], off offset:0
	global_load_dwordx2 v[152:153], v[206:207], off offset:16
	global_load_dwordx2 v[154:155], v[206:207], off offset:32
	global_load_dwordx2 v[156:157], v[206:207], off offset:48
	global_load_dwordx2 v[192:193], v[206:207], off offset:64
	global_load_dwordx2 v[194:195], v[206:207], off offset:80
	global_load_dwordx2 v[198:199], v[206:207], off offset:96
	global_load_dwordx2 v[200:201], v[206:207], off offset:112
	global_load_dwordx2 v[112:113], v[206:207], off offset:128
	global_load_dwordx2 v[114:115], v[206:207], off offset:144
	global_load_dwordx2 v[202:203], v[206:207], off offset:160
	global_load_dwordx2 v[204:205], v[206:207], off offset:176
	global_load_dwordx2 v[240:241], v[206:207], off offset:192
	global_load_dwordx2 v[242:243], v[206:207], off offset:208
	global_load_dwordx2 v[146:147], v[206:207], off offset:224
	global_load_dwordx2 v[148:149], v[206:207], off offset:240
	s_waitcnt vmcnt(0)
.Lp5v3_head:
	s_add_u32 s100, s94, 0x4000
	s_mov_b32 s101, 0
	ds_read_b32 v158, v141
	v_lshl_add_u64 v[212:213], v[142:143], 0, s[100:101]
	s_waitcnt vmcnt(24)
	v_mfma_f32_32x32x16_bf16 v[64:79], v[170:173], v[80:83], 0
	global_load_dwordx4 v[170:173], v[212:213], off
	s_waitcnt vmcnt(24)
	v_mfma_f32_32x32x16_bf16 v[64:79], v[174:177], v[84:87], v[64:79]
	global_load_dwordx4 v[174:177], v[212:213], off offset:32
	s_waitcnt vmcnt(24)
	v_mfma_f32_32x32x16_bf16 v[64:79], v[178:181], v[88:91], v[64:79]
	global_load_dwordx4 v[178:181], v[212:213], off offset:64
	s_waitcnt vmcnt(24)
	v_mfma_f32_32x32x16_bf16 v[64:79], v[220:223], v[92:95], v[64:79]
	global_load_dwordx4 v[220:223], v[212:213], off offset:96
	s_waitcnt vmcnt(24)
	v_mfma_f32_32x32x16_bf16 v[64:79], v[224:227], v[96:99], v[64:79]
	global_load_dwordx4 v[224:227], v[212:213], off offset:128
	s_waitcnt vmcnt(24)
	v_mfma_f32_32x32x16_bf16 v[64:79], v[228:231], v[100:103], v[64:79]
	global_load_dwordx4 v[228:231], v[212:213], off offset:160
	s_waitcnt vmcnt(24)
	v_mfma_f32_32x32x16_bf16 v[64:79], v[232:235], v[104:107], v[64:79]
	global_load_dwordx4 v[232:235], v[212:213], off offset:192
	s_waitcnt vmcnt(24)
	v_mfma_f32_32x32x16_bf16 v[64:79], v[208:211], v[108:111], v[64:79]
	global_load_dwordx4 v[208:211], v[212:213], off offset:224
	s_waitcnt lgkmcnt(0)
	v_mul_f32_e32 v164, 0x3fb8aa3b, v158
	v_exp_f32_e32 v165, v164
	v_mov_b32_e32 v158, v164
	s_nop 8
	v_mul_f32_e32 v64, v165, v64
	v_mul_f32_e32 v65, v165, v65
	v_mul_f32_e32 v66, v165, v66
	v_mul_f32_e32 v67, v165, v67
	v_mul_f32_e32 v68, v165, v68
	v_mul_f32_e32 v69, v165, v69
	v_mul_f32_e32 v70, v165, v70
	v_mul_f32_e32 v71, v165, v71
	v_mul_f32_e32 v72, v165, v72
	v_mul_f32_e32 v73, v165, v73
	v_mul_f32_e32 v74, v165, v74
	v_mul_f32_e32 v75, v165, v75
	v_mul_f32_e32 v76, v165, v76
	v_mul_f32_e32 v77, v165, v77
	v_mul_f32_e32 v78, v165, v78
	v_mul_f32_e32 v79, v165, v79
	ds_read_b128 v[236:239], v161 offset:4096
	ds_read_b128 v[250:253], v161 offset:4128
	s_waitcnt lgkmcnt(1)
	v_add_f32_e32 v164, v158, v236
	v_add_f32_e32 v165, v158, v237
	v_add_f32_e32 v244, v158, v238
	v_add_f32_e32 v245, v158, v239
	v_exp_f32_e32 v164, v164
	v_exp_f32_e32 v165, v165
	v_exp_f32_e32 v244, v244
	v_exp_f32_e32 v245, v245
	ds_read_b128 v[236:239], v161 offset:4160
	v_mul_f32_e32 v212, v0, v164
	v_mul_f32_e32 v213, v1, v165
	v_mul_f32_e32 v214, v2, v244
	v_mul_f32_e32 v215, v3, v245
	s_waitcnt lgkmcnt(1)
; #define LAS __attribute__((address_space(3)))
; __device__ __forceinline__ f32x16 mfma32(bf16x8 a, bf16x8 b, f32x16 c) { return __builtin_amdgcn_mfma_f32_32x32x16_bf16(a, b, c, 0, 0, 0); }
; __device__ __forceinline__ void phase_ssd_y(const PT& p, LAS unsigned char* lds, int tid, int lane, int wave) {
;     ...
; #pragma unroll
;             for (int sb = 0; sb < 4; ++sb) {
;                 if (sb <= lb) {
;                     f32x16 mm;
; #pragma unroll
;                     for (int qd = 0; qd < 4; ++qd) {
;                         const int s0 = sb * 32 + 8 * qd + 4 * h;
;                         const f32x4 as = *(const LAS f32x4*)(acum + r * 128 + s0), ds = *(const LAS f32x4*)(dtt + r * 128 + s0);
; #pragma unroll
;                         for (int j = 0; j < 4; ++j) { const float v = X[sb][4 * qd + j] * __expf(al - as[j]) * ds[j]; mm[4 * qd + j] = (s0 + j < l) ? v : ((s0 + j == l) ? v + dsk : 0.f); }
;                     }
; #pragma unroll
;                     for (int s2 = 0; s2 < 2; ++s2) acc = mfma32(ld_frag8x2(xrow + sb * 32 + 16 * s2), pack_frag(mm, s2), acc);
	v_add_f32_e32 v164, v158, v250
	v_add_f32_e32 v165, v158, v251
	v_add_f32_e32 v244, v158, v252
	v_add_f32_e32 v245, v158, v253
	v_exp_f32_e32 v164, v164
	v_exp_f32_e32 v165, v165
	v_exp_f32_e32 v244, v244
	v_exp_f32_e32 v245, v245
	ds_read_b128 v[250:253], v161 offset:4192
	v_mul_f32_e32 v216, v4, v164
	v_mul_f32_e32 v217, v5, v165
	v_mul_f32_e32 v218, v6, v244
	v_mul_f32_e32 v219, v7, v245
	v_cvt_pk_bf16_f32 v212, v212, v213
	v_cvt_pk_bf16_f32 v213, v214, v215
	v_cvt_pk_bf16_f32 v214, v216, v217
	v_cvt_pk_bf16_f32 v215, v218, v219
	s_nop 0
	s_waitcnt vmcnt(21)
	v_mfma_f32_32x32x16_bf16 v[64:79], v[150:153], v[212:215], v[64:79]
	s_waitcnt lgkmcnt(1)
	v_add_f32_e32 v164, v158, v236
	v_add_f32_e32 v165, v158, v237
	v_add_f32_e32 v244, v158, v238
	v_add_f32_e32 v245, v158, v239
	v_exp_f32_e32 v164, v164
	v_exp_f32_e32 v165, v165
	v_exp_f32_e32 v244, v244
	v_exp_f32_e32 v245, v245
	v_mul_f32_e32 v212, v8, v164
	v_mul_f32_e32 v213, v9, v165
	v_mul_f32_e32 v214, v10, v244
	v_mul_f32_e32 v215, v11, v245
	s_waitcnt lgkmcnt(0)
	v_add_f32_e32 v164, v158, v250
	v_add_f32_e32 v165, v158, v251
	v_add_f32_e32 v244, v158, v252
	v_add_f32_e32 v245, v158, v253
	v_exp_f32_e32 v164, v164
	v_exp_f32_e32 v165, v165
	v_exp_f32_e32 v244, v244
	v_exp_f32_e32 v245, v245
	v_mul_f32_e32 v216, v12, v164
	v_mul_f32_e32 v217, v13, v165
	v_mul_f32_e32 v218, v14, v244
	v_mul_f32_e32 v219, v15, v245
	v_cvt_pk_bf16_f32 v212, v212, v213
	v_cvt_pk_bf16_f32 v213, v214, v215
	v_cvt_pk_bf16_f32 v214, v216, v217
	v_cvt_pk_bf16_f32 v215, v218, v219
	s_nop 0
	s_nop 0
	v_mfma_f32_32x32x16_bf16 v[64:79], v[154:157], v[212:215], v[64:79]
	global_load_dwordx2 v[150:151], v[184:185], off offset:0
	global_load_dwordx2 v[152:153], v[184:185], off offset:16
	global_load_dwordx2 v[154:155], v[184:185], off offset:32
	global_load_dwordx2 v[156:157], v[184:185], off offset:48
	ds_read_b128 v[236:239], v161 offset:4224
	ds_read_b128 v[250:253], v161 offset:4256
	s_waitcnt lgkmcnt(1)
	v_add_f32_e32 v164, v158, v236
	v_add_f32_e32 v165, v158, v237
	v_add_f32_e32 v244, v158, v238
	v_add_f32_e32 v245, v158, v239
	v_exp_f32_e32 v164, v164
	v_exp_f32_e32 v165, v165
	v_exp_f32_e32 v244, v244
	v_exp_f32_e32 v245, v245
	ds_read_b128 v[236:239], v161 offset:4288
	v_mul_f32_e32 v212, v16, v164
	v_mul_f32_e32 v213, v17, v165
	v_mul_f32_e32 v214, v18, v244
	v_mul_f32_e32 v215, v19, v245
	s_waitcnt lgkmcnt(1)
	v_add_f32_e32 v164, v158, v250
	v_add_f32_e32 v165, v158, v251
	v_add_f32_e32 v244, v158, v252
	v_add_f32_e32 v245, v158, v253
	v_exp_f32_e32 v164, v164
	v_exp_f32_e32 v165, v165
	v_exp_f32_e32 v244, v244
	v_exp_f32_e32 v245, v245
	ds_read_b128 v[250:253], v161 offset:4320
	v_mul_f32_e32 v216, v20, v164
	v_mul_f32_e32 v217, v21, v165
	v_mul_f32_e32 v218, v22, v244
	v_mul_f32_e32 v219, v23, v245
	v_cvt_pk_bf16_f32 v212, v212, v213
	v_cvt_pk_bf16_f32 v213, v214, v215
	v_cvt_pk_bf16_f32 v214, v216, v217
	v_cvt_pk_bf16_f32 v215, v218, v219
	s_nop 0
	s_waitcnt vmcnt(21)
	v_mfma_f32_32x32x16_bf16 v[64:79], v[192:195], v[212:215], v[64:79]
	s_waitcnt lgkmcnt(1)
	v_add_f32_e32 v164, v158, v236
	v_add_f32_e32 v165, v158, v237
	v_add_f32_e32 v244, v158, v238
	v_add_f32_e32 v245, v158, v239
	v_exp_f32_e32 v164, v164
	v_exp_f32_e32 v165, v165
	v_exp_f32_e32 v244, v244
	v_exp_f32_e32 v245, v245
	v_mul_f32_e32 v212, v24, v164
	v_mul_f32_e32 v213, v25, v165
	v_mul_f32_e32 v214, v26, v244
	v_mul_f32_e32 v215, v27, v245
	s_waitcnt lgkmcnt(0)
	v_add_f32_e32 v164, v158, v250
	v_add_f32_e32 v165, v158, v251
	v_add_f32_e32 v244, v158, v252
	v_add_f32_e32 v245, v158, v253
	v_exp_f32_e32 v164, v164
	v_exp_f32_e32 v165, v165
	v_exp_f32_e32 v244, v244
	v_exp_f32_e32 v245, v245
	v_mul_f32_e32 v216, v28, v164
	v_mul_f32_e32 v217, v29, v165
	v_mul_f32_e32 v218, v30, v244
	v_mul_f32_e32 v219, v31, v245
	v_cvt_pk_bf16_f32 v212, v212, v213
	v_cvt_pk_bf16_f32 v213, v214, v215
	v_cvt_pk_bf16_f32 v214, v216, v217
	v_cvt_pk_bf16_f32 v215, v218, v219
	s_nop 0
	s_nop 0
	v_mfma_f32_32x32x16_bf16 v[64:79], v[198:201], v[212:215], v[64:79]
	global_load_dwordx2 v[192:193], v[184:185], off offset:64
	global_load_dwordx2 v[194:195], v[184:185], off offset:80
	global_load_dwordx2 v[198:199], v[184:185], off offset:96
	global_load_dwordx2 v[200:201], v[184:185], off offset:112
	ds_read_b128 v[236:239], v161 offset:4352
	ds_read_b128 v[250:253], v161 offset:4384
	s_waitcnt lgkmcnt(1)
	v_add_f32_e32 v164, v158, v236
	v_add_f32_e32 v165, v158, v237
	v_add_f32_e32 v244, v158, v238
	v_add_f32_e32 v245, v158, v239
	v_exp_f32_e32 v164, v164
	v_exp_f32_e32 v165, v165
	v_exp_f32_e32 v244, v244
	v_exp_f32_e32 v245, v245
	ds_read_b128 v[236:239], v161 offset:4416
	v_mul_f32_e32 v212, v48, v164
	v_mul_f32_e32 v213, v49, v165
	v_mul_f32_e32 v214, v50, v244
	v_mul_f32_e32 v215, v51, v245
	s_waitcnt lgkmcnt(1)
	v_add_f32_e32 v164, v158, v250
	v_add_f32_e32 v165, v158, v251
	v_add_f32_e32 v244, v158, v252
	v_add_f32_e32 v245, v158, v253
	v_exp_f32_e32 v164, v164
	v_exp_f32_e32 v165, v165
	v_exp_f32_e32 v244, v244
	v_exp_f32_e32 v245, v245
	ds_read_b128 v[250:253], v161 offset:4448
	v_mul_f32_e32 v216, v52, v164
	v_mul_f32_e32 v217, v53, v165
	v_mul_f32_e32 v218, v54, v244
	v_mul_f32_e32 v219, v55, v245
	v_cvt_pk_bf16_f32 v212, v212, v213
	v_cvt_pk_bf16_f32 v213, v214, v215
	v_cvt_pk_bf16_f32 v214, v216, v217
	v_cvt_pk_bf16_f32 v215, v218, v219
	s_nop 0
	s_waitcnt vmcnt(21)
	v_mfma_f32_32x32x16_bf16 v[64:79], v[112:115], v[212:215], v[64:79]
	s_waitcnt lgkmcnt(1)
	v_add_f32_e32 v164, v158, v236
	v_add_f32_e32 v165, v158, v237
	v_add_f32_e32 v244, v158, v238
	v_add_f32_e32 v245, v158, v239
	v_exp_f32_e32 v164, v164
	v_exp_f32_e32 v165, v165
	v_exp_f32_e32 v244, v244
	v_exp_f32_e32 v245, v245
	v_mul_f32_e32 v212, v56, v164
	v_mul_f32_e32 v213, v57, v165
	v_mul_f32_e32 v214, v58, v244
	v_mul_f32_e32 v215, v59, v245
	s_waitcnt lgkmcnt(0)
; #define LAS __attribute__((address_space(3)))
; __device__ __forceinline__ f32x16 mfma32(bf16x8 a, bf16x8 b, f32x16 c) { return __builtin_amdgcn_mfma_f32_32x32x16_bf16(a, b, c, 0, 0, 0); }
; __device__ __forceinline__ void phase_ssd_y(const PT& p, LAS unsigned char* lds, int tid, int lane, int wave) {
;     ...
;             for (int sb = 0; sb < 4; ++sb) {
;                 if (sb <= lb) {
;                     f32x16 mm;
; #pragma unroll
;                     for (int qd = 0; qd < 4; ++qd) {
;                         const int s0 = sb * 32 + 8 * qd + 4 * h;
;                         const f32x4 as = *(const LAS f32x4*)(acum + r * 128 + s0), ds = *(const LAS f32x4*)(dtt + r * 128 + s0);
; #pragma unroll
;                         for (int j = 0; j < 4; ++j) { const float v = X[sb][4 * qd + j] * __expf(al - as[j]) * ds[j]; mm[4 * qd + j] = (s0 + j < l) ? v : ((s0 + j == l) ? v + dsk : 0.f); }
;                     }
; #pragma unroll
;                     for (int s2 = 0; s2 < 2; ++s2) acc = mfma32(ld_frag8x2(xrow + sb * 32 + 16 * s2), pack_frag(mm, s2), acc);
	v_add_f32_e32 v164, v158, v250
	v_add_f32_e32 v165, v158, v251
	v_add_f32_e32 v244, v158, v252
	v_add_f32_e32 v245, v158, v253
	v_exp_f32_e32 v164, v164
	v_exp_f32_e32 v165, v165
	v_exp_f32_e32 v244, v244
	v_exp_f32_e32 v245, v245
	v_mul_f32_e32 v216, v60, v164
	v_mul_f32_e32 v217, v61, v165
	v_mul_f32_e32 v218, v62, v244
	v_mul_f32_e32 v219, v63, v245
	v_cvt_pk_bf16_f32 v212, v212, v213
	v_cvt_pk_bf16_f32 v213, v214, v215
	v_cvt_pk_bf16_f32 v214, v216, v217
	v_cvt_pk_bf16_f32 v215, v218, v219
	s_nop 0
	s_nop 0
	v_mfma_f32_32x32x16_bf16 v[64:79], v[202:205], v[212:215], v[64:79]
	global_load_dwordx2 v[112:113], v[184:185], off offset:128
	global_load_dwordx2 v[114:115], v[184:185], off offset:144
	global_load_dwordx2 v[202:203], v[184:185], off offset:160
	global_load_dwordx2 v[204:205], v[184:185], off offset:176
	ds_read_b128 v[236:239], v161 offset:4480
	ds_read_b128 v[250:253], v161 offset:4512
	s_waitcnt lgkmcnt(1)
	v_add_f32_e32 v164, v158, v236
	v_add_f32_e32 v165, v158, v237
	v_add_f32_e32 v244, v158, v238
	v_add_f32_e32 v245, v158, v239
	v_exp_f32_e32 v164, v164
	v_exp_f32_e32 v165, v165
	v_exp_f32_e32 v244, v244
	v_exp_f32_e32 v245, v245
	ds_read_b128 v[236:239], v161 offset:4544
	v_mul_f32_e32 v212, v32, v164
	v_mul_f32_e32 v213, v33, v165
	v_mul_f32_e32 v214, v34, v244
	v_mul_f32_e32 v215, v35, v245
	s_waitcnt lgkmcnt(1)
	v_add_f32_e32 v164, v158, v250
	v_add_f32_e32 v165, v158, v251
	v_add_f32_e32 v244, v158, v252
	v_add_f32_e32 v245, v158, v253
	v_exp_f32_e32 v164, v164
	v_exp_f32_e32 v165, v165
	v_exp_f32_e32 v244, v244
	v_exp_f32_e32 v245, v245
	ds_read_b128 v[250:253], v161 offset:4576
	v_mul_f32_e32 v216, v36, v164
	v_mul_f32_e32 v217, v37, v165
	v_mul_f32_e32 v218, v38, v244
	v_mul_f32_e32 v219, v39, v245
	s_waitcnt vmcnt(24)
	v_add_f32_e32 v169, v212, v159
	v_add_f32_e32 v183, v213, v159
	v_cmp_eq_u32_e32 vcc, 0, v160
	v_cmp_eq_u32_e64 s[100:101], 1, v160
	s_nop 0
	v_cndmask_b32_e32 v169, 0, v169, vcc
	v_cndmask_b32_e64 v183, 0, v183, s[100:101]
	v_cmp_lt_i32_e32 vcc, 0, v160
	v_cmp_lt_i32_e64 s[100:101], 1, v160
	s_nop 0
	v_cndmask_b32_e32 v212, v169, v212, vcc
	v_cndmask_b32_e64 v213, v183, v213, s[100:101]
	v_add_f32_e32 v169, v214, v159
	v_add_f32_e32 v183, v215, v159
	v_cmp_eq_u32_e32 vcc, 2, v160
	v_cmp_eq_u32_e64 s[100:101], 3, v160
	s_nop 0
	v_cndmask_b32_e32 v169, 0, v169, vcc
	v_cndmask_b32_e64 v183, 0, v183, s[100:101]
	v_cmp_lt_i32_e32 vcc, 2, v160
	v_cmp_lt_i32_e64 s[100:101], 3, v160
	s_nop 0
	v_cndmask_b32_e32 v214, v169, v214, vcc
	v_cndmask_b32_e64 v215, v183, v215, s[100:101]
	v_add_f32_e32 v169, v216, v159
	v_add_f32_e32 v183, v217, v159
	v_cmp_eq_u32_e32 vcc, 8, v160
	v_cmp_eq_u32_e64 s[100:101], 9, v160
	s_nop 0
	v_cndmask_b32_e32 v169, 0, v169, vcc
	v_cndmask_b32_e64 v183, 0, v183, s[100:101]
	v_cmp_lt_i32_e32 vcc, 8, v160
	v_cmp_lt_i32_e64 s[100:101], 9, v160
	s_nop 0
	v_cndmask_b32_e32 v216, v169, v216, vcc
	v_cndmask_b32_e64 v217, v183, v217, s[100:101]
	v_add_f32_e32 v169, v218, v159
	v_add_f32_e32 v183, v219, v159
	v_cmp_eq_u32_e32 vcc, 10, v160
	v_cmp_eq_u32_e64 s[100:101], 11, v160
	s_nop 0
	v_cndmask_b32_e32 v169, 0, v169, vcc
	v_cndmask_b32_e64 v183, 0, v183, s[100:101]
	v_cmp_lt_i32_e32 vcc, 10, v160
	v_cmp_lt_i32_e64 s[100:101], 11, v160
	s_nop 0
	v_cndmask_b32_e32 v218, v169, v218, vcc
	v_cndmask_b32_e64 v219, v183, v219, s[100:101]
	v_cvt_pk_bf16_f32 v212, v212, v213
	v_cvt_pk_bf16_f32 v213, v214, v215
	v_cvt_pk_bf16_f32 v214, v216, v217
	v_cvt_pk_bf16_f32 v215, v218, v219
	s_nop 0
	s_waitcnt vmcnt(20)
	v_mfma_f32_32x32x16_bf16 v[64:79], v[240:243], v[212:215], v[64:79]
	s_waitcnt lgkmcnt(1)
	v_add_f32_e32 v164, v158, v236
	v_add_f32_e32 v165, v158, v237
	v_add_f32_e32 v244, v158, v238
	v_add_f32_e32 v245, v158, v239
	v_exp_f32_e32 v164, v164
	v_exp_f32_e32 v165, v165
	v_exp_f32_e32 v244, v244
	v_exp_f32_e32 v245, v245
	v_mul_f32_e32 v212, v40, v164
	v_mul_f32_e32 v213, v41, v165
	v_mul_f32_e32 v214, v42, v244
	v_mul_f32_e32 v215, v43, v245
	s_waitcnt lgkmcnt(0)
	v_add_f32_e32 v164, v158, v250
	v_add_f32_e32 v165, v158, v251
	v_add_f32_e32 v244, v158, v252
	v_add_f32_e32 v245, v158, v253
	v_exp_f32_e32 v164, v164
	v_exp_f32_e32 v165, v165
	v_exp_f32_e32 v244, v244
	v_exp_f32_e32 v245, v245
	v_mul_f32_e32 v216, v44, v164
	v_mul_f32_e32 v217, v45, v165
	v_mul_f32_e32 v218, v46, v244
	v_mul_f32_e32 v219, v47, v245
	v_add_f32_e32 v169, v212, v159
	v_add_f32_e32 v183, v213, v159
	v_cmp_eq_u32_e32 vcc, 16, v160
	v_cmp_eq_u32_e64 s[100:101], 17, v160
	s_nop 0
	v_cndmask_b32_e32 v169, 0, v169, vcc
	v_cndmask_b32_e64 v183, 0, v183, s[100:101]
	v_cmp_lt_i32_e32 vcc, 16, v160
	v_cmp_lt_i32_e64 s[100:101], 17, v160
	s_nop 0
	v_cndmask_b32_e32 v212, v169, v212, vcc
	v_cndmask_b32_e64 v213, v183, v213, s[100:101]
	v_add_f32_e32 v169, v214, v159
	v_add_f32_e32 v183, v215, v159
	v_cmp_eq_u32_e32 vcc, 18, v160
	v_cmp_eq_u32_e64 s[100:101], 19, v160
	s_nop 0
	v_cndmask_b32_e32 v169, 0, v169, vcc
	v_cndmask_b32_e64 v183, 0, v183, s[100:101]
	v_cmp_lt_i32_e32 vcc, 18, v160
	v_cmp_lt_i32_e64 s[100:101], 19, v160
	s_nop 0
	v_cndmask_b32_e32 v214, v169, v214, vcc
	v_cndmask_b32_e64 v215, v183, v215, s[100:101]
	v_add_f32_e32 v169, v216, v159
	v_add_f32_e32 v183, v217, v159
	v_cmp_eq_u32_e32 vcc, 24, v160
	v_cmp_eq_u32_e64 s[100:101], 25, v160
	s_nop 0
	v_cndmask_b32_e32 v169, 0, v169, vcc
	v_cndmask_b32_e64 v183, 0, v183, s[100:101]
	v_cmp_lt_i32_e32 vcc, 24, v160
	v_cmp_lt_i32_e64 s[100:101], 25, v160
	s_nop 0
	v_cndmask_b32_e32 v216, v169, v216, vcc
	v_cndmask_b32_e64 v217, v183, v217, s[100:101]
	v_add_f32_e32 v169, v218, v159
	v_add_f32_e32 v183, v219, v159
	v_cmp_eq_u32_e32 vcc, 26, v160
	v_cmp_eq_u32_e64 s[100:101], 27, v160
	s_nop 0
	v_cndmask_b32_e32 v169, 0, v169, vcc
	v_cndmask_b32_e64 v183, 0, v183, s[100:101]
	v_cmp_lt_i32_e32 vcc, 26, v160
	v_cmp_lt_i32_e64 s[100:101], 27, v160
	s_nop 0
	v_cndmask_b32_e32 v218, v169, v218, vcc
	v_cndmask_b32_e64 v219, v183, v219, s[100:101]
	s_cmp_eq_u32 s94, 0x1c000
	s_cselect_b32 s100, 0, 4
	s_add_u32 s84, s84, s100
	s_addc_u32 s85, s85, 0
	v_mov_b32_e32 v164, 0
	global_load_dword v159, v164, s[84:85]
	v_cvt_pk_bf16_f32 v212, v212, v213
	v_cvt_pk_bf16_f32 v213, v214, v215
	v_cvt_pk_bf16_f32 v214, v216, v217
	v_cvt_pk_bf16_f32 v215, v218, v219
	s_nop 0
	s_nop 0
	v_mfma_f32_32x32x16_bf16 v[64:79], v[146:149], v[212:215], v[64:79]
	global_load_dwordx2 v[240:241], v[184:185], off offset:192
	global_load_dwordx2 v[242:243], v[184:185], off offset:208
	global_load_dwordx2 v[146:147], v[184:185], off offset:224
	global_load_dwordx2 v[148:149], v[184:185], off offset:240
	s_nop 10
	ds_read_b64 v[216:217], v162 offset:0
	s_waitcnt lgkmcnt(0)
; #define LAS __attribute__((address_space(3)))
; __device__ __forceinline__ float bflo(unsigned u) { return __uint_as_float(u << 16); }
; __device__ __forceinline__ float bfhi(unsigned u) { return __uint_as_float(u & 0xffff0000u); }
; __device__ __forceinline__ f32x16 mfma32(bf16x8 a, bf16x8 b, f32x16 c) { return __builtin_amdgcn_mfma_f32_32x32x16_bf16(a, b, c, 0, 0, 0); }
; __device__ __forceinline__ void phase_ssd_y(const PT& p, LAS unsigned char* lds, int tid, int lane, int wave) {
;     ...
;             const bf16* pp = PV + ((size_t)(bc * 32 + hh) * 64 + pb * 32 + r32) * 128 + 8 * h;
; #pragma unroll
;             for (int st = 0; st < 8; ++st) acc = mfma32(ld_frag16(pp + 16 * st), cf[st], acc);
;     ...
; #pragma unroll
;             for (int qd = 0; qd < 4; ++qd) {
;                 LAS u32x2* yp = (LAS u32x2*)(tile + l * SY_TP + (r * 64 + pb * 32 + 8 * qd + 4 * h) * 2); const u32x2 zz = *yp;
;                 const float y0 = acc[4 * qd] * bflo(zz.x), y1 = acc[4 * qd + 1] * bfhi(zz.x);
;                 const float y2 = acc[4 * qd + 2] * bflo(zz.y), y3 = acc[4 * qd + 3] * bfhi(zz.y);
;                 ssq += (y0 * y0 + y1 * y1) + (y2 * y2 + y3 * y3);
;                 u32x2 w; w.x = pk2(y0, y1); w.y = pk2(y2, y3); *yp = w;
;             }
;         }
	v_lshlrev_b32_e32 v169, 16, v216
	v_and_b32_e32 v183, 0xffff0000, v216
	v_lshlrev_b32_e32 v254, 16, v217
	v_and_b32_e32 v255, 0xffff0000, v217
	v_mul_f32_e32 v169, v64, v169
	v_mul_f32_e32 v183, v65, v183
	v_mul_f32_e32 v254, v66, v254
	v_mul_f32_e32 v255, v67, v255
	v_mul_f32_e32 v164, v169, v169
	v_mul_f32_e32 v165, v254, v254
	v_fmac_f32_e32 v164, v183, v183
	v_fmac_f32_e32 v165, v255, v255
	v_cvt_pk_bf16_f32 v216, v169, v183
	v_cvt_pk_bf16_f32 v217, v254, v255
	v_add_f32_e32 v164, v164, v165
	ds_write_b64 v162, v[216:217] offset:0
	v_add_f32_e32 v126, v126, v164
	ds_read_b64 v[216:217], v162 offset:16
	s_waitcnt lgkmcnt(0)
	v_lshlrev_b32_e32 v169, 16, v216
	v_and_b32_e32 v183, 0xffff0000, v216
	v_lshlrev_b32_e32 v254, 16, v217
	v_and_b32_e32 v255, 0xffff0000, v217
	v_mul_f32_e32 v169, v68, v169
	v_mul_f32_e32 v183, v69, v183
	v_mul_f32_e32 v254, v70, v254
	v_mul_f32_e32 v255, v71, v255
	v_mul_f32_e32 v164, v169, v169
	v_mul_f32_e32 v165, v254, v254
	v_fmac_f32_e32 v164, v183, v183
	v_fmac_f32_e32 v165, v255, v255
	v_cvt_pk_bf16_f32 v216, v169, v183
	v_cvt_pk_bf16_f32 v217, v254, v255
	v_add_f32_e32 v164, v164, v165
	ds_write_b64 v162, v[216:217] offset:16
	v_add_f32_e32 v126, v126, v164
	ds_read_b64 v[216:217], v162 offset:32
	s_waitcnt lgkmcnt(0)
	v_lshlrev_b32_e32 v169, 16, v216
	v_and_b32_e32 v183, 0xffff0000, v216
	v_lshlrev_b32_e32 v254, 16, v217
	v_and_b32_e32 v255, 0xffff0000, v217
	v_mul_f32_e32 v169, v72, v169
	v_mul_f32_e32 v183, v73, v183
	v_mul_f32_e32 v254, v74, v254
	v_mul_f32_e32 v255, v75, v255
	v_mul_f32_e32 v164, v169, v169
	v_mul_f32_e32 v165, v254, v254
	v_fmac_f32_e32 v164, v183, v183
	v_fmac_f32_e32 v165, v255, v255
	v_cvt_pk_bf16_f32 v216, v169, v183
	v_cvt_pk_bf16_f32 v217, v254, v255
	v_add_f32_e32 v164, v164, v165
	ds_write_b64 v162, v[216:217] offset:32
	v_add_f32_e32 v126, v126, v164
	ds_read_b64 v[216:217], v162 offset:48
	s_waitcnt lgkmcnt(0)
	v_lshlrev_b32_e32 v169, 16, v216
	v_and_b32_e32 v183, 0xffff0000, v216
	v_lshlrev_b32_e32 v254, 16, v217
	v_and_b32_e32 v255, 0xffff0000, v217
	v_mul_f32_e32 v169, v76, v169
	v_mul_f32_e32 v183, v77, v183
	v_mul_f32_e32 v254, v78, v254
	v_mul_f32_e32 v255, v79, v255
	v_mul_f32_e32 v164, v169, v169
	v_mul_f32_e32 v165, v254, v254
	v_fmac_f32_e32 v164, v183, v183
	v_fmac_f32_e32 v165, v255, v255
	v_cvt_pk_bf16_f32 v216, v169, v183
	v_cvt_pk_bf16_f32 v217, v254, v255
	v_add_f32_e32 v164, v164, v165
	ds_write_b64 v162, v[216:217] offset:48
	v_add_f32_e32 v126, v126, v164
	v_add_u32_e32 v161, 0x200, v161
	v_add_u32_e32 v141, 0x200, v141
	v_add_u32_e32 v162, 0x80, v162
	v_mov_b32_e32 v206, v184
	v_mov_b32_e32 v207, v185
	v_add_co_u32_e32 v184, vcc, 0x4000, v184
	s_nop 1
	v_addc_co_u32_e32 v185, vcc, 0, v185, vcc
	s_add_u32 s94, s94, 0x4000
	s_cmp_eq_u32 s94, 0x20000
	s_cbranch_scc0 .Lp5v3_head
	s_branch .Lp5v_exit
.Lp5v2:
	v_lshl_add_u64 v[212:213], v[142:143], 0, s[94:95]
	v_lshl_add_u64 v[206:207], v[144:145], 0, s[94:95]
	v_mov_b32_e32 v164, 0
	v_add_co_u32_e32 v206, vcc, 0x1a900000, v206
	s_nop 1
	v_addc_co_u32_e32 v207, vcc, 0, v207, vcc
	v_add_co_u32_e32 v184, vcc, 0x4000, v206
	s_nop 1
	v_addc_co_u32_e32 v185, vcc, 0, v207, vcc
	global_load_dword v159, v164, s[84:85]
	global_load_dwordx4 v[170:173], v[212:213], off
	global_load_dwordx4 v[174:177], v[212:213], off offset:32
	global_load_dwordx4 v[178:181], v[212:213], off offset:64
	global_load_dwordx4 v[220:223], v[212:213], off offset:96
	global_load_dwordx4 v[224:227], v[212:213], off offset:128
	global_load_dwordx4 v[228:231], v[212:213], off offset:160
	global_load_dwordx4 v[232:235], v[212:213], off offset:192
	global_load_dwordx4 v[208:211], v[212:213], off offset:224
	global_load_dwordx2 v[150:151], v[206:207], off offset:0
	global_load_dwordx2 v[152:153], v[206:207], off offset:16
	global_load_dwordx2 v[154:155], v[206:207], off offset:32
	global_load_dwordx2 v[156:157], v[206:207], off offset:48
	global_load_dwordx2 v[192:193], v[206:207], off offset:64
	global_load_dwordx2 v[194:195], v[206:207], off offset:80
	global_load_dwordx2 v[198:199], v[206:207], off offset:96
	global_load_dwordx2 v[200:201], v[206:207], off offset:112
	global_load_dwordx2 v[112:113], v[206:207], off offset:128
	global_load_dwordx2 v[114:115], v[206:207], off offset:144
	global_load_dwordx2 v[202:203], v[206:207], off offset:160
	global_load_dwordx2 v[204:205], v[206:207], off offset:176
	s_waitcnt vmcnt(0)
; #define LAS __attribute__((address_space(3)))
; __device__ __forceinline__ f32x16 mfma32(bf16x8 a, bf16x8 b, f32x16 c) { return __builtin_amdgcn_mfma_f32_32x32x16_bf16(a, b, c, 0, 0, 0); }
; __device__ __forceinline__ void phase_ssd_y(const PT& p, LAS unsigned char* lds, int tid, int lane, int wave) {
;     ...
;             const bf16* pp = PV + ((size_t)(bc * 32 + hh) * 64 + pb * 32 + r32) * 128 + 8 * h;
; #pragma unroll
;             for (int st = 0; st < 8; ++st) acc = mfma32(ld_frag16(pp + 16 * st), cf[st], acc);
;             const float al = acum[r * 128 + l]; const float el = __expf(al); const float dsk = p.in[11][hh];
; #pragma unroll
;             for (int i = 0; i < 16; ++i) acc[i] *= el;
;             const bf16* xrow = xT + ((size_t)bc * 2048 + hh * 64 + pb * 32 + r32) * 128 + 4 * h;
; #pragma unroll
;             for (int sb = 0; sb < 4; ++sb) {
;                 if (sb <= lb) {
;                     f32x16 mm;
; #pragma unroll
;                     for (int qd = 0; qd < 4; ++qd) {
;                         const int s0 = sb * 32 + 8 * qd + 4 * h;
;                         const f32x4 as = *(const LAS f32x4*)(acum + r * 128 + s0), ds = *(const LAS f32x4*)(dtt + r * 128 + s0);
; #pragma unroll
;                         for (int j = 0; j < 4; ++j) { const float v = X[sb][4 * qd + j] * __expf(al - as[j]) * ds[j]; mm[4 * qd + j] = (s0 + j < l) ? v : ((s0 + j == l) ? v + dsk : 0.f); }
;                     }
; #pragma unroll
;                     for (int s2 = 0; s2 < 2; ++s2) acc = mfma32(ld_frag8x2(xrow + sb * 32 + 16 * s2), pack_frag(mm, s2), acc);
.Lp5v2_head:
	s_add_u32 s100, s94, 0x4000
	s_mov_b32 s101, 0
	ds_read_b32 v158, v141
	v_lshl_add_u64 v[212:213], v[142:143], 0, s[100:101]
	s_waitcnt vmcnt(20)
	v_mfma_f32_32x32x16_bf16 v[64:79], v[170:173], v[80:83], 0
	global_load_dwordx4 v[170:173], v[212:213], off
	s_waitcnt vmcnt(20)
	v_mfma_f32_32x32x16_bf16 v[64:79], v[174:177], v[84:87], v[64:79]
	global_load_dwordx4 v[174:177], v[212:213], off offset:32
	s_waitcnt vmcnt(20)
	v_mfma_f32_32x32x16_bf16 v[64:79], v[178:181], v[88:91], v[64:79]
	global_load_dwordx4 v[178:181], v[212:213], off offset:64
	s_waitcnt vmcnt(20)
	v_mfma_f32_32x32x16_bf16 v[64:79], v[220:223], v[92:95], v[64:79]
	global_load_dwordx4 v[220:223], v[212:213], off offset:96
	s_waitcnt vmcnt(20)
	v_mfma_f32_32x32x16_bf16 v[64:79], v[224:227], v[96:99], v[64:79]
	global_load_dwordx4 v[224:227], v[212:213], off offset:128
	s_waitcnt vmcnt(20)
	v_mfma_f32_32x32x16_bf16 v[64:79], v[228:231], v[100:103], v[64:79]
	global_load_dwordx4 v[228:231], v[212:213], off offset:160
	s_waitcnt vmcnt(20)
	v_mfma_f32_32x32x16_bf16 v[64:79], v[232:235], v[104:107], v[64:79]
	global_load_dwordx4 v[232:235], v[212:213], off offset:192
	s_waitcnt vmcnt(20)
	v_mfma_f32_32x32x16_bf16 v[64:79], v[208:211], v[108:111], v[64:79]
	global_load_dwordx4 v[208:211], v[212:213], off offset:224
	s_waitcnt lgkmcnt(0)
	v_mul_f32_e32 v164, 0x3fb8aa3b, v158
	v_exp_f32_e32 v165, v164
	v_mov_b32_e32 v158, v164
	s_nop 8
	v_mul_f32_e32 v64, v165, v64
	v_mul_f32_e32 v65, v165, v65
	v_mul_f32_e32 v66, v165, v66
	v_mul_f32_e32 v67, v165, v67
	v_mul_f32_e32 v68, v165, v68
	v_mul_f32_e32 v69, v165, v69
	v_mul_f32_e32 v70, v165, v70
	v_mul_f32_e32 v71, v165, v71
	v_mul_f32_e32 v72, v165, v72
	v_mul_f32_e32 v73, v165, v73
	v_mul_f32_e32 v74, v165, v74
	v_mul_f32_e32 v75, v165, v75
	v_mul_f32_e32 v76, v165, v76
	v_mul_f32_e32 v77, v165, v77
	v_mul_f32_e32 v78, v165, v78
	v_mul_f32_e32 v79, v165, v79
	ds_read_b128 v[236:239], v161 offset:4096
	ds_read_b128 v[250:253], v161 offset:4128
	s_waitcnt lgkmcnt(1)
	v_add_f32_e32 v164, v158, v236
	v_add_f32_e32 v165, v158, v237
	v_add_f32_e32 v244, v158, v238
	v_add_f32_e32 v245, v158, v239
	v_exp_f32_e32 v164, v164
	v_exp_f32_e32 v165, v165
	v_exp_f32_e32 v244, v244
	v_exp_f32_e32 v245, v245
	ds_read_b128 v[236:239], v161 offset:4160
	v_mul_f32_e32 v212, v0, v164
	v_mul_f32_e32 v213, v1, v165
	v_mul_f32_e32 v214, v2, v244
	v_mul_f32_e32 v215, v3, v245
	s_waitcnt lgkmcnt(1)
	v_add_f32_e32 v164, v158, v250
	v_add_f32_e32 v165, v158, v251
	v_add_f32_e32 v244, v158, v252
	v_add_f32_e32 v245, v158, v253
	v_exp_f32_e32 v164, v164
	v_exp_f32_e32 v165, v165
	v_exp_f32_e32 v244, v244
	v_exp_f32_e32 v245, v245
	ds_read_b128 v[250:253], v161 offset:4192
	v_mul_f32_e32 v216, v4, v164
	v_mul_f32_e32 v217, v5, v165
	v_mul_f32_e32 v218, v6, v244
	v_mul_f32_e32 v219, v7, v245
	v_cvt_pk_bf16_f32 v212, v212, v213
	v_cvt_pk_bf16_f32 v213, v214, v215
	v_cvt_pk_bf16_f32 v214, v216, v217
	v_cvt_pk_bf16_f32 v215, v218, v219
	s_nop 0
	s_waitcnt vmcnt(17)
	v_mfma_f32_32x32x16_bf16 v[64:79], v[150:153], v[212:215], v[64:79]
	s_waitcnt lgkmcnt(1)
	v_add_f32_e32 v164, v158, v236
	v_add_f32_e32 v165, v158, v237
	v_add_f32_e32 v244, v158, v238
	v_add_f32_e32 v245, v158, v239
	v_exp_f32_e32 v164, v164
	v_exp_f32_e32 v165, v165
	v_exp_f32_e32 v244, v244
	v_exp_f32_e32 v245, v245
	v_mul_f32_e32 v212, v8, v164
	v_mul_f32_e32 v213, v9, v165
	v_mul_f32_e32 v214, v10, v244
	v_mul_f32_e32 v215, v11, v245
	s_waitcnt lgkmcnt(0)
	v_add_f32_e32 v164, v158, v250
	v_add_f32_e32 v165, v158, v251
	v_add_f32_e32 v244, v158, v252
	v_add_f32_e32 v245, v158, v253
	v_exp_f32_e32 v164, v164
	v_exp_f32_e32 v165, v165
	v_exp_f32_e32 v244, v244
	v_exp_f32_e32 v245, v245
	v_mul_f32_e32 v216, v12, v164
	v_mul_f32_e32 v217, v13, v165
	v_mul_f32_e32 v218, v14, v244
	v_mul_f32_e32 v219, v15, v245
	v_cvt_pk_bf16_f32 v212, v212, v213
	v_cvt_pk_bf16_f32 v213, v214, v215
	v_cvt_pk_bf16_f32 v214, v216, v217
	v_cvt_pk_bf16_f32 v215, v218, v219
	s_nop 0
	s_nop 0
	v_mfma_f32_32x32x16_bf16 v[64:79], v[154:157], v[212:215], v[64:79]
	global_load_dwordx2 v[150:151], v[184:185], off offset:0
	global_load_dwordx2 v[152:153], v[184:185], off offset:16
	global_load_dwordx2 v[154:155], v[184:185], off offset:32
	global_load_dwordx2 v[156:157], v[184:185], off offset:48
	ds_read_b128 v[236:239], v161 offset:4224
	ds_read_b128 v[250:253], v161 offset:4256
	s_waitcnt lgkmcnt(1)
	v_add_f32_e32 v164, v158, v236
	v_add_f32_e32 v165, v158, v237
	v_add_f32_e32 v244, v158, v238
	v_add_f32_e32 v245, v158, v239
	v_exp_f32_e32 v164, v164
	v_exp_f32_e32 v165, v165
	v_exp_f32_e32 v244, v244
	v_exp_f32_e32 v245, v245
	ds_read_b128 v[236:239], v161 offset:4288
	v_mul_f32_e32 v212, v16, v164
	v_mul_f32_e32 v213, v17, v165
	v_mul_f32_e32 v214, v18, v244
	v_mul_f32_e32 v215, v19, v245
	s_waitcnt lgkmcnt(1)
	v_add_f32_e32 v164, v158, v250
	v_add_f32_e32 v165, v158, v251
	v_add_f32_e32 v244, v158, v252
	v_add_f32_e32 v245, v158, v253
	v_exp_f32_e32 v164, v164
	v_exp_f32_e32 v165, v165
	v_exp_f32_e32 v244, v244
	v_exp_f32_e32 v245, v245
	ds_read_b128 v[250:253], v161 offset:4320
	v_mul_f32_e32 v216, v20, v164
	v_mul_f32_e32 v217, v21, v165
	v_mul_f32_e32 v218, v22, v244
	v_mul_f32_e32 v219, v23, v245
	v_cvt_pk_bf16_f32 v212, v212, v213
	v_cvt_pk_bf16_f32 v213, v214, v215
	v_cvt_pk_bf16_f32 v214, v216, v217
	v_cvt_pk_bf16_f32 v215, v218, v219
	s_nop 0
	s_waitcnt vmcnt(17)
	v_mfma_f32_32x32x16_bf16 v[64:79], v[192:195], v[212:215], v[64:79]
	s_waitcnt lgkmcnt(1)
; #define LAS __attribute__((address_space(3)))
; __device__ __forceinline__ f32x16 mfma32(bf16x8 a, bf16x8 b, f32x16 c) { return __builtin_amdgcn_mfma_f32_32x32x16_bf16(a, b, c, 0, 0, 0); }
; __device__ __forceinline__ void phase_ssd_y(const PT& p, LAS unsigned char* lds, int tid, int lane, int wave) {
;     ...
;             for (int sb = 0; sb < 4; ++sb) {
;                 if (sb <= lb) {
;                     f32x16 mm;
; #pragma unroll
;                     for (int qd = 0; qd < 4; ++qd) {
;                         const int s0 = sb * 32 + 8 * qd + 4 * h;
;                         const f32x4 as = *(const LAS f32x4*)(acum + r * 128 + s0), ds = *(const LAS f32x4*)(dtt + r * 128 + s0);
; #pragma unroll
;                         for (int j = 0; j < 4; ++j) { const float v = X[sb][4 * qd + j] * __expf(al - as[j]) * ds[j]; mm[4 * qd + j] = (s0 + j < l) ? v : ((s0 + j == l) ? v + dsk : 0.f); }
;                     }
; #pragma unroll
;                     for (int s2 = 0; s2 < 2; ++s2) acc = mfma32(ld_frag8x2(xrow + sb * 32 + 16 * s2), pack_frag(mm, s2), acc);
	v_add_f32_e32 v164, v158, v236
	v_add_f32_e32 v165, v158, v237
	v_add_f32_e32 v244, v158, v238
	v_add_f32_e32 v245, v158, v239
	v_exp_f32_e32 v164, v164
	v_exp_f32_e32 v165, v165
	v_exp_f32_e32 v244, v244
	v_exp_f32_e32 v245, v245
	v_mul_f32_e32 v212, v24, v164
	v_mul_f32_e32 v213, v25, v165
	v_mul_f32_e32 v214, v26, v244
	v_mul_f32_e32 v215, v27, v245
	s_waitcnt lgkmcnt(0)
	v_add_f32_e32 v164, v158, v250
	v_add_f32_e32 v165, v158, v251
	v_add_f32_e32 v244, v158, v252
	v_add_f32_e32 v245, v158, v253
	v_exp_f32_e32 v164, v164
	v_exp_f32_e32 v165, v165
	v_exp_f32_e32 v244, v244
	v_exp_f32_e32 v245, v245
	v_mul_f32_e32 v216, v28, v164
	v_mul_f32_e32 v217, v29, v165
	v_mul_f32_e32 v218, v30, v244
	v_mul_f32_e32 v219, v31, v245
	v_cvt_pk_bf16_f32 v212, v212, v213
	v_cvt_pk_bf16_f32 v213, v214, v215
	v_cvt_pk_bf16_f32 v214, v216, v217
	v_cvt_pk_bf16_f32 v215, v218, v219
	s_nop 0
	s_nop 0
	v_mfma_f32_32x32x16_bf16 v[64:79], v[198:201], v[212:215], v[64:79]
	global_load_dwordx2 v[192:193], v[184:185], off offset:64
	global_load_dwordx2 v[194:195], v[184:185], off offset:80
	global_load_dwordx2 v[198:199], v[184:185], off offset:96
	global_load_dwordx2 v[200:201], v[184:185], off offset:112
	ds_read_b128 v[236:239], v161 offset:4352
	ds_read_b128 v[250:253], v161 offset:4384
	s_waitcnt lgkmcnt(1)
	v_add_f32_e32 v164, v158, v236
	v_add_f32_e32 v165, v158, v237
	v_add_f32_e32 v244, v158, v238
	v_add_f32_e32 v245, v158, v239
	v_exp_f32_e32 v164, v164
	v_exp_f32_e32 v165, v165
	v_exp_f32_e32 v244, v244
	v_exp_f32_e32 v245, v245
	ds_read_b128 v[236:239], v161 offset:4416
	v_mul_f32_e32 v212, v48, v164
	v_mul_f32_e32 v213, v49, v165
	v_mul_f32_e32 v214, v50, v244
	v_mul_f32_e32 v215, v51, v245
	s_waitcnt lgkmcnt(1)
	v_add_f32_e32 v164, v158, v250
	v_add_f32_e32 v165, v158, v251
	v_add_f32_e32 v244, v158, v252
	v_add_f32_e32 v245, v158, v253
	v_exp_f32_e32 v164, v164
	v_exp_f32_e32 v165, v165
	v_exp_f32_e32 v244, v244
	v_exp_f32_e32 v245, v245
	ds_read_b128 v[250:253], v161 offset:4448
	v_mul_f32_e32 v216, v52, v164
	v_mul_f32_e32 v217, v53, v165
	v_mul_f32_e32 v218, v54, v244
	v_mul_f32_e32 v219, v55, v245
	s_waitcnt vmcnt(20)
	v_add_f32_e32 v169, v212, v159
	v_add_f32_e32 v183, v213, v159
	v_cmp_eq_u32_e32 vcc, 0, v160
	v_cmp_eq_u32_e64 s[100:101], 1, v160
	s_nop 0
	v_cndmask_b32_e32 v169, 0, v169, vcc
	v_cndmask_b32_e64 v183, 0, v183, s[100:101]
	v_cmp_lt_i32_e32 vcc, 0, v160
	v_cmp_lt_i32_e64 s[100:101], 1, v160
	s_nop 0
	v_cndmask_b32_e32 v212, v169, v212, vcc
	v_cndmask_b32_e64 v213, v183, v213, s[100:101]
	v_add_f32_e32 v169, v214, v159
	v_add_f32_e32 v183, v215, v159
	v_cmp_eq_u32_e32 vcc, 2, v160
	v_cmp_eq_u32_e64 s[100:101], 3, v160
	s_nop 0
	v_cndmask_b32_e32 v169, 0, v169, vcc
	v_cndmask_b32_e64 v183, 0, v183, s[100:101]
	v_cmp_lt_i32_e32 vcc, 2, v160
	v_cmp_lt_i32_e64 s[100:101], 3, v160
	s_nop 0
	v_cndmask_b32_e32 v214, v169, v214, vcc
	v_cndmask_b32_e64 v215, v183, v215, s[100:101]
	v_add_f32_e32 v169, v216, v159
	v_add_f32_e32 v183, v217, v159
	v_cmp_eq_u32_e32 vcc, 8, v160
	v_cmp_eq_u32_e64 s[100:101], 9, v160
	s_nop 0
	v_cndmask_b32_e32 v169, 0, v169, vcc
	v_cndmask_b32_e64 v183, 0, v183, s[100:101]
	v_cmp_lt_i32_e32 vcc, 8, v160
	v_cmp_lt_i32_e64 s[100:101], 9, v160
	s_nop 0
	v_cndmask_b32_e32 v216, v169, v216, vcc
	v_cndmask_b32_e64 v217, v183, v217, s[100:101]
	v_add_f32_e32 v169, v218, v159
	v_add_f32_e32 v183, v219, v159
	v_cmp_eq_u32_e32 vcc, 10, v160
	v_cmp_eq_u32_e64 s[100:101], 11, v160
	s_nop 0
	v_cndmask_b32_e32 v169, 0, v169, vcc
	v_cndmask_b32_e64 v183, 0, v183, s[100:101]
	v_cmp_lt_i32_e32 vcc, 10, v160
	v_cmp_lt_i32_e64 s[100:101], 11, v160
	s_nop 0
	v_cndmask_b32_e32 v218, v169, v218, vcc
	v_cndmask_b32_e64 v219, v183, v219, s[100:101]
	v_cvt_pk_bf16_f32 v212, v212, v213
	v_cvt_pk_bf16_f32 v213, v214, v215
	v_cvt_pk_bf16_f32 v214, v216, v217
	v_cvt_pk_bf16_f32 v215, v218, v219
	s_nop 0
	s_waitcnt vmcnt(16)
	v_mfma_f32_32x32x16_bf16 v[64:79], v[112:115], v[212:215], v[64:79]
	s_waitcnt lgkmcnt(1)
	v_add_f32_e32 v164, v158, v236
	v_add_f32_e32 v165, v158, v237
	v_add_f32_e32 v244, v158, v238
	v_add_f32_e32 v245, v158, v239
	v_exp_f32_e32 v164, v164
	v_exp_f32_e32 v165, v165
	v_exp_f32_e32 v244, v244
	v_exp_f32_e32 v245, v245
	v_mul_f32_e32 v212, v56, v164
	v_mul_f32_e32 v213, v57, v165
	v_mul_f32_e32 v214, v58, v244
	v_mul_f32_e32 v215, v59, v245
	s_waitcnt lgkmcnt(0)
; #define LAS __attribute__((address_space(3)))
; __device__ __forceinline__ float bflo(unsigned u) { return __uint_as_float(u << 16); }
; __device__ __forceinline__ float bfhi(unsigned u) { return __uint_as_float(u & 0xffff0000u); }
; __device__ __forceinline__ f32x16 mfma32(bf16x8 a, bf16x8 b, f32x16 c) { return __builtin_amdgcn_mfma_f32_32x32x16_bf16(a, b, c, 0, 0, 0); }
; __device__ __forceinline__ void phase_ssd_y(const PT& p, LAS unsigned char* lds, int tid, int lane, int wave) {
;     ...
;             for (int sb = 0; sb < 4; ++sb) {
;                 if (sb <= lb) {
;                     f32x16 mm;
; #pragma unroll
;                     for (int qd = 0; qd < 4; ++qd) {
;                         const int s0 = sb * 32 + 8 * qd + 4 * h;
;                         const f32x4 as = *(const LAS f32x4*)(acum + r * 128 + s0), ds = *(const LAS f32x4*)(dtt + r * 128 + s0);
; #pragma unroll
;                         for (int j = 0; j < 4; ++j) { const float v = X[sb][4 * qd + j] * __expf(al - as[j]) * ds[j]; mm[4 * qd + j] = (s0 + j < l) ? v : ((s0 + j == l) ? v + dsk : 0.f); }
;                     }
; #pragma unroll
;                     for (int s2 = 0; s2 < 2; ++s2) acc = mfma32(ld_frag8x2(xrow + sb * 32 + 16 * s2), pack_frag(mm, s2), acc);
;                 }
;             }
; #pragma unroll
;             for (int qd = 0; qd < 4; ++qd) {
;                 LAS u32x2* yp = (LAS u32x2*)(tile + l * SY_TP + (r * 64 + pb * 32 + 8 * qd + 4 * h) * 2); const u32x2 zz = *yp;
;                 const float y0 = acc[4 * qd] * bflo(zz.x), y1 = acc[4 * qd + 1] * bfhi(zz.x);
;                 const float y2 = acc[4 * qd + 2] * bflo(zz.y), y3 = acc[4 * qd + 3] * bfhi(zz.y);
;                 ssq += (y0 * y0 + y1 * y1) + (y2 * y2 + y3 * y3);
;                 u32x2 w; w.x = pk2(y0, y1); w.y = pk2(y2, y3); *yp = w;
;             }
;         }
	v_add_f32_e32 v164, v158, v250
	v_add_f32_e32 v165, v158, v251
	v_add_f32_e32 v244, v158, v252
	v_add_f32_e32 v245, v158, v253
	v_exp_f32_e32 v164, v164
	v_exp_f32_e32 v165, v165
	v_exp_f32_e32 v244, v244
	v_exp_f32_e32 v245, v245
	v_mul_f32_e32 v216, v60, v164
	v_mul_f32_e32 v217, v61, v165
	v_mul_f32_e32 v218, v62, v244
	v_mul_f32_e32 v219, v63, v245
	v_add_f32_e32 v169, v212, v159
	v_add_f32_e32 v183, v213, v159
	v_cmp_eq_u32_e32 vcc, 16, v160
	v_cmp_eq_u32_e64 s[100:101], 17, v160
	s_nop 0
	v_cndmask_b32_e32 v169, 0, v169, vcc
	v_cndmask_b32_e64 v183, 0, v183, s[100:101]
	v_cmp_lt_i32_e32 vcc, 16, v160
	v_cmp_lt_i32_e64 s[100:101], 17, v160
	s_nop 0
	v_cndmask_b32_e32 v212, v169, v212, vcc
	v_cndmask_b32_e64 v213, v183, v213, s[100:101]
	v_add_f32_e32 v169, v214, v159
	v_add_f32_e32 v183, v215, v159
	v_cmp_eq_u32_e32 vcc, 18, v160
	v_cmp_eq_u32_e64 s[100:101], 19, v160
	s_nop 0
	v_cndmask_b32_e32 v169, 0, v169, vcc
	v_cndmask_b32_e64 v183, 0, v183, s[100:101]
	v_cmp_lt_i32_e32 vcc, 18, v160
	v_cmp_lt_i32_e64 s[100:101], 19, v160
	s_nop 0
	v_cndmask_b32_e32 v214, v169, v214, vcc
	v_cndmask_b32_e64 v215, v183, v215, s[100:101]
	v_add_f32_e32 v169, v216, v159
	v_add_f32_e32 v183, v217, v159
	v_cmp_eq_u32_e32 vcc, 24, v160
	v_cmp_eq_u32_e64 s[100:101], 25, v160
	s_nop 0
	v_cndmask_b32_e32 v169, 0, v169, vcc
	v_cndmask_b32_e64 v183, 0, v183, s[100:101]
	v_cmp_lt_i32_e32 vcc, 24, v160
	v_cmp_lt_i32_e64 s[100:101], 25, v160
	s_nop 0
	v_cndmask_b32_e32 v216, v169, v216, vcc
	v_cndmask_b32_e64 v217, v183, v217, s[100:101]
	v_add_f32_e32 v169, v218, v159
	v_add_f32_e32 v183, v219, v159
	v_cmp_eq_u32_e32 vcc, 26, v160
	v_cmp_eq_u32_e64 s[100:101], 27, v160
	s_nop 0
	v_cndmask_b32_e32 v169, 0, v169, vcc
	v_cndmask_b32_e64 v183, 0, v183, s[100:101]
	v_cmp_lt_i32_e32 vcc, 26, v160
	v_cmp_lt_i32_e64 s[100:101], 27, v160
	s_nop 0
	v_cndmask_b32_e32 v218, v169, v218, vcc
	v_cndmask_b32_e64 v219, v183, v219, s[100:101]
	s_cmp_eq_u32 s94, 0x1c000
	s_cselect_b32 s100, 0, 4
	s_add_u32 s84, s84, s100
	s_addc_u32 s85, s85, 0
	v_mov_b32_e32 v164, 0
	global_load_dword v159, v164, s[84:85]
	v_cvt_pk_bf16_f32 v212, v212, v213
	v_cvt_pk_bf16_f32 v213, v214, v215
	v_cvt_pk_bf16_f32 v214, v216, v217
	v_cvt_pk_bf16_f32 v215, v218, v219
	s_nop 0
	s_nop 0
	v_mfma_f32_32x32x16_bf16 v[64:79], v[202:205], v[212:215], v[64:79]
	global_load_dwordx2 v[112:113], v[184:185], off offset:128
	global_load_dwordx2 v[114:115], v[184:185], off offset:144
	global_load_dwordx2 v[202:203], v[184:185], off offset:160
	global_load_dwordx2 v[204:205], v[184:185], off offset:176
	s_nop 10
	ds_read_b64 v[216:217], v162 offset:0
	s_waitcnt lgkmcnt(0)
	v_lshlrev_b32_e32 v169, 16, v216
	v_and_b32_e32 v183, 0xffff0000, v216
	v_lshlrev_b32_e32 v254, 16, v217
	v_and_b32_e32 v255, 0xffff0000, v217
	v_mul_f32_e32 v169, v64, v169
	v_mul_f32_e32 v183, v65, v183
	v_mul_f32_e32 v254, v66, v254
	v_mul_f32_e32 v255, v67, v255
	v_mul_f32_e32 v164, v169, v169
	v_mul_f32_e32 v165, v254, v254
	v_fmac_f32_e32 v164, v183, v183
	v_fmac_f32_e32 v165, v255, v255
	v_cvt_pk_bf16_f32 v216, v169, v183
	v_cvt_pk_bf16_f32 v217, v254, v255
	v_add_f32_e32 v164, v164, v165
	ds_write_b64 v162, v[216:217] offset:0
	v_add_f32_e32 v126, v126, v164
	ds_read_b64 v[216:217], v162 offset:16
	s_waitcnt lgkmcnt(0)
	v_lshlrev_b32_e32 v169, 16, v216
	v_and_b32_e32 v183, 0xffff0000, v216
	v_lshlrev_b32_e32 v254, 16, v217
	v_and_b32_e32 v255, 0xffff0000, v217
	v_mul_f32_e32 v169, v68, v169
	v_mul_f32_e32 v183, v69, v183
	v_mul_f32_e32 v254, v70, v254
	v_mul_f32_e32 v255, v71, v255
	v_mul_f32_e32 v164, v169, v169
	v_mul_f32_e32 v165, v254, v254
	v_fmac_f32_e32 v164, v183, v183
	v_fmac_f32_e32 v165, v255, v255
	v_cvt_pk_bf16_f32 v216, v169, v183
	v_cvt_pk_bf16_f32 v217, v254, v255
	v_add_f32_e32 v164, v164, v165
	ds_write_b64 v162, v[216:217] offset:16
	v_add_f32_e32 v126, v126, v164
	ds_read_b64 v[216:217], v162 offset:32
	s_waitcnt lgkmcnt(0)
	v_lshlrev_b32_e32 v169, 16, v216
	v_and_b32_e32 v183, 0xffff0000, v216
	v_lshlrev_b32_e32 v254, 16, v217
	v_and_b32_e32 v255, 0xffff0000, v217
	v_mul_f32_e32 v169, v72, v169
	v_mul_f32_e32 v183, v73, v183
	v_mul_f32_e32 v254, v74, v254
	v_mul_f32_e32 v255, v75, v255
	v_mul_f32_e32 v164, v169, v169
	v_mul_f32_e32 v165, v254, v254
	v_fmac_f32_e32 v164, v183, v183
	v_fmac_f32_e32 v165, v255, v255
	v_cvt_pk_bf16_f32 v216, v169, v183
	v_cvt_pk_bf16_f32 v217, v254, v255
	v_add_f32_e32 v164, v164, v165
	ds_write_b64 v162, v[216:217] offset:32
	v_add_f32_e32 v126, v126, v164
	ds_read_b64 v[216:217], v162 offset:48
	s_waitcnt lgkmcnt(0)
	v_lshlrev_b32_e32 v169, 16, v216
	v_and_b32_e32 v183, 0xffff0000, v216
	v_lshlrev_b32_e32 v254, 16, v217
	v_and_b32_e32 v255, 0xffff0000, v217
	v_mul_f32_e32 v169, v76, v169
	v_mul_f32_e32 v183, v77, v183
	v_mul_f32_e32 v254, v78, v254
	v_mul_f32_e32 v255, v79, v255
	v_mul_f32_e32 v164, v169, v169
	v_mul_f32_e32 v165, v254, v254
	v_fmac_f32_e32 v164, v183, v183
	v_fmac_f32_e32 v165, v255, v255
	v_cvt_pk_bf16_f32 v216, v169, v183
	v_cvt_pk_bf16_f32 v217, v254, v255
	v_add_f32_e32 v164, v164, v165
	ds_write_b64 v162, v[216:217] offset:48
	v_add_f32_e32 v126, v126, v164
	v_add_u32_e32 v161, 0x200, v161
	v_add_u32_e32 v141, 0x200, v141
	v_add_u32_e32 v162, 0x80, v162
	v_mov_b32_e32 v206, v184
	v_mov_b32_e32 v207, v185
	v_add_co_u32_e32 v184, vcc, 0x4000, v184
	s_nop 1
	v_addc_co_u32_e32 v185, vcc, 0, v185, vcc
	s_add_u32 s94, s94, 0x4000
	s_cmp_eq_u32 s94, 0x20000
	s_cbranch_scc0 .Lp5v2_head
	s_branch .Lp5v_exit
; #define LAS __attribute__((address_space(3)))
; __device__ __forceinline__ f32x16 mfma32(bf16x8 a, bf16x8 b, f32x16 c) { return __builtin_amdgcn_mfma_f32_32x32x16_bf16(a, b, c, 0, 0, 0); }
; __device__ __forceinline__ void phase_ssd_y(const PT& p, LAS unsigned char* lds, int tid, int lane, int wave) {
;     ...
;             const bf16* pp = PV + ((size_t)(bc * 32 + hh) * 64 + pb * 32 + r32) * 128 + 8 * h;
; #pragma unroll
;             for (int st = 0; st < 8; ++st) acc = mfma32(ld_frag16(pp + 16 * st), cf[st], acc);
;             const float al = acum[r * 128 + l]; const float el = __expf(al); const float dsk = p.in[11][hh];
; #pragma unroll
;             for (int i = 0; i < 16; ++i) acc[i] *= el;
;             const bf16* xrow = xT + ((size_t)bc * 2048 + hh * 64 + pb * 32 + r32) * 128 + 4 * h;
; #pragma unroll
;             for (int sb = 0; sb < 4; ++sb) {
;                 if (sb <= lb) {
;                     f32x16 mm;
; #pragma unroll
;                     for (int qd = 0; qd < 4; ++qd) {
;                         const int s0 = sb * 32 + 8 * qd + 4 * h;
;                         const f32x4 as = *(const LAS f32x4*)(acum + r * 128 + s0), ds = *(const LAS f32x4*)(dtt + r * 128 + s0);
; #pragma unroll
;                         for (int j = 0; j < 4; ++j) { const float v = X[sb][4 * qd + j] * __expf(al - as[j]) * ds[j]; mm[4 * qd + j] = (s0 + j < l) ? v : ((s0 + j == l) ? v + dsk : 0.f); }
;                     }
; #pragma unroll
;                     for (int s2 = 0; s2 < 2; ++s2) acc = mfma32(ld_frag8x2(xrow + sb * 32 + 16 * s2), pack_frag(mm, s2), acc);
.Lp5v1:
	v_lshl_add_u64 v[212:213], v[142:143], 0, s[94:95]
	v_lshl_add_u64 v[206:207], v[144:145], 0, s[94:95]
	v_mov_b32_e32 v164, 0
	v_add_co_u32_e32 v206, vcc, 0x1a900000, v206
	s_nop 1
	v_addc_co_u32_e32 v207, vcc, 0, v207, vcc
	v_add_co_u32_e32 v184, vcc, 0x4000, v206
	s_nop 1
	v_addc_co_u32_e32 v185, vcc, 0, v207, vcc
	global_load_dword v159, v164, s[84:85]
	global_load_dwordx4 v[170:173], v[212:213], off
	global_load_dwordx4 v[174:177], v[212:213], off offset:32
	global_load_dwordx4 v[178:181], v[212:213], off offset:64
	global_load_dwordx4 v[220:223], v[212:213], off offset:96
	global_load_dwordx4 v[224:227], v[212:213], off offset:128
	global_load_dwordx4 v[228:231], v[212:213], off offset:160
	global_load_dwordx4 v[232:235], v[212:213], off offset:192
	global_load_dwordx4 v[208:211], v[212:213], off offset:224
	global_load_dwordx2 v[150:151], v[206:207], off offset:0
	global_load_dwordx2 v[152:153], v[206:207], off offset:16
	global_load_dwordx2 v[154:155], v[206:207], off offset:32
	global_load_dwordx2 v[156:157], v[206:207], off offset:48
	global_load_dwordx2 v[192:193], v[206:207], off offset:64
	global_load_dwordx2 v[194:195], v[206:207], off offset:80
	global_load_dwordx2 v[198:199], v[206:207], off offset:96
	global_load_dwordx2 v[200:201], v[206:207], off offset:112
	s_waitcnt vmcnt(0)
.Lp5v1_head:
	s_add_u32 s100, s94, 0x4000
	s_mov_b32 s101, 0
	ds_read_b32 v158, v141
	v_lshl_add_u64 v[212:213], v[142:143], 0, s[100:101]
	s_waitcnt vmcnt(16)
	v_mfma_f32_32x32x16_bf16 v[64:79], v[170:173], v[80:83], 0
	global_load_dwordx4 v[170:173], v[212:213], off
	s_waitcnt vmcnt(16)
	v_mfma_f32_32x32x16_bf16 v[64:79], v[174:177], v[84:87], v[64:79]
	global_load_dwordx4 v[174:177], v[212:213], off offset:32
	s_waitcnt vmcnt(16)
	v_mfma_f32_32x32x16_bf16 v[64:79], v[178:181], v[88:91], v[64:79]
	global_load_dwordx4 v[178:181], v[212:213], off offset:64
	s_waitcnt vmcnt(16)
	v_mfma_f32_32x32x16_bf16 v[64:79], v[220:223], v[92:95], v[64:79]
	global_load_dwordx4 v[220:223], v[212:213], off offset:96
	s_waitcnt vmcnt(16)
	v_mfma_f32_32x32x16_bf16 v[64:79], v[224:227], v[96:99], v[64:79]
	global_load_dwordx4 v[224:227], v[212:213], off offset:128
	s_waitcnt vmcnt(16)
	v_mfma_f32_32x32x16_bf16 v[64:79], v[228:231], v[100:103], v[64:79]
	global_load_dwordx4 v[228:231], v[212:213], off offset:160
	s_waitcnt vmcnt(16)
	v_mfma_f32_32x32x16_bf16 v[64:79], v[232:235], v[104:107], v[64:79]
	global_load_dwordx4 v[232:235], v[212:213], off offset:192
	s_waitcnt vmcnt(16)
	v_mfma_f32_32x32x16_bf16 v[64:79], v[208:211], v[108:111], v[64:79]
	global_load_dwordx4 v[208:211], v[212:213], off offset:224
	s_waitcnt lgkmcnt(0)
	v_mul_f32_e32 v164, 0x3fb8aa3b, v158
	v_exp_f32_e32 v165, v164
	v_mov_b32_e32 v158, v164
	s_nop 8
	v_mul_f32_e32 v64, v165, v64
	v_mul_f32_e32 v65, v165, v65
	v_mul_f32_e32 v66, v165, v66
	v_mul_f32_e32 v67, v165, v67
	v_mul_f32_e32 v68, v165, v68
	v_mul_f32_e32 v69, v165, v69
	v_mul_f32_e32 v70, v165, v70
	v_mul_f32_e32 v71, v165, v71
	v_mul_f32_e32 v72, v165, v72
	v_mul_f32_e32 v73, v165, v73
	v_mul_f32_e32 v74, v165, v74
	v_mul_f32_e32 v75, v165, v75
	v_mul_f32_e32 v76, v165, v76
	v_mul_f32_e32 v77, v165, v77
	v_mul_f32_e32 v78, v165, v78
	v_mul_f32_e32 v79, v165, v79
	ds_read_b128 v[236:239], v161 offset:4096
	ds_read_b128 v[250:253], v161 offset:4128
	s_waitcnt lgkmcnt(1)
	v_add_f32_e32 v164, v158, v236
	v_add_f32_e32 v165, v158, v237
	v_add_f32_e32 v244, v158, v238
	v_add_f32_e32 v245, v158, v239
	v_exp_f32_e32 v164, v164
	v_exp_f32_e32 v165, v165
	v_exp_f32_e32 v244, v244
	v_exp_f32_e32 v245, v245
	ds_read_b128 v[236:239], v161 offset:4160
	v_mul_f32_e32 v212, v0, v164
	v_mul_f32_e32 v213, v1, v165
	v_mul_f32_e32 v214, v2, v244
	v_mul_f32_e32 v215, v3, v245
	s_waitcnt lgkmcnt(1)
	v_add_f32_e32 v164, v158, v250
	v_add_f32_e32 v165, v158, v251
	v_add_f32_e32 v244, v158, v252
	v_add_f32_e32 v245, v158, v253
	v_exp_f32_e32 v164, v164
	v_exp_f32_e32 v165, v165
	v_exp_f32_e32 v244, v244
	v_exp_f32_e32 v245, v245
	ds_read_b128 v[250:253], v161 offset:4192
	v_mul_f32_e32 v216, v4, v164
	v_mul_f32_e32 v217, v5, v165
	v_mul_f32_e32 v218, v6, v244
	v_mul_f32_e32 v219, v7, v245
	v_cvt_pk_bf16_f32 v212, v212, v213
	v_cvt_pk_bf16_f32 v213, v214, v215
	v_cvt_pk_bf16_f32 v214, v216, v217
	v_cvt_pk_bf16_f32 v215, v218, v219
	s_nop 0
	s_waitcnt vmcnt(13)
	v_mfma_f32_32x32x16_bf16 v[64:79], v[150:153], v[212:215], v[64:79]
	s_waitcnt lgkmcnt(1)
	v_add_f32_e32 v164, v158, v236
	v_add_f32_e32 v165, v158, v237
	v_add_f32_e32 v244, v158, v238
	v_add_f32_e32 v245, v158, v239
	v_exp_f32_e32 v164, v164
	v_exp_f32_e32 v165, v165
	v_exp_f32_e32 v244, v244
	v_exp_f32_e32 v245, v245
	v_mul_f32_e32 v212, v8, v164
	v_mul_f32_e32 v213, v9, v165
	v_mul_f32_e32 v214, v10, v244
	v_mul_f32_e32 v215, v11, v245
	s_waitcnt lgkmcnt(0)
	v_add_f32_e32 v164, v158, v250
	v_add_f32_e32 v165, v158, v251
	v_add_f32_e32 v244, v158, v252
	v_add_f32_e32 v245, v158, v253
	v_exp_f32_e32 v164, v164
	v_exp_f32_e32 v165, v165
	v_exp_f32_e32 v244, v244
	v_exp_f32_e32 v245, v245
	v_mul_f32_e32 v216, v12, v164
	v_mul_f32_e32 v217, v13, v165
	v_mul_f32_e32 v218, v14, v244
	v_mul_f32_e32 v219, v15, v245
	v_cvt_pk_bf16_f32 v212, v212, v213
	v_cvt_pk_bf16_f32 v213, v214, v215
	v_cvt_pk_bf16_f32 v214, v216, v217
	v_cvt_pk_bf16_f32 v215, v218, v219
	s_nop 0
	s_nop 0
	v_mfma_f32_32x32x16_bf16 v[64:79], v[154:157], v[212:215], v[64:79]
	global_load_dwordx2 v[150:151], v[184:185], off offset:0
	global_load_dwordx2 v[152:153], v[184:185], off offset:16
	global_load_dwordx2 v[154:155], v[184:185], off offset:32
	global_load_dwordx2 v[156:157], v[184:185], off offset:48
	ds_read_b128 v[236:239], v161 offset:4224
	ds_read_b128 v[250:253], v161 offset:4256
	s_waitcnt lgkmcnt(1)
; #define LAS __attribute__((address_space(3)))
; __device__ __forceinline__ f32x16 mfma32(bf16x8 a, bf16x8 b, f32x16 c) { return __builtin_amdgcn_mfma_f32_32x32x16_bf16(a, b, c, 0, 0, 0); }
; __device__ __forceinline__ void phase_ssd_y(const PT& p, LAS unsigned char* lds, int tid, int lane, int wave) {
;     ...
;             for (int sb = 0; sb < 4; ++sb) {
;                 if (sb <= lb) {
;                     f32x16 mm;
; #pragma unroll
;                     for (int qd = 0; qd < 4; ++qd) {
;                         const int s0 = sb * 32 + 8 * qd + 4 * h;
;                         const f32x4 as = *(const LAS f32x4*)(acum + r * 128 + s0), ds = *(const LAS f32x4*)(dtt + r * 128 + s0);
; #pragma unroll
;                         for (int j = 0; j < 4; ++j) { const float v = X[sb][4 * qd + j] * __expf(al - as[j]) * ds[j]; mm[4 * qd + j] = (s0 + j < l) ? v : ((s0 + j == l) ? v + dsk : 0.f); }
;                     }
; #pragma unroll
;                     for (int s2 = 0; s2 < 2; ++s2) acc = mfma32(ld_frag8x2(xrow + sb * 32 + 16 * s2), pack_frag(mm, s2), acc);
	v_add_f32_e32 v164, v158, v236
	v_add_f32_e32 v165, v158, v237
	v_add_f32_e32 v244, v158, v238
	v_add_f32_e32 v245, v158, v239
	v_exp_f32_e32 v164, v164
	v_exp_f32_e32 v165, v165
	v_exp_f32_e32 v244, v244
	v_exp_f32_e32 v245, v245
	ds_read_b128 v[236:239], v161 offset:4288
	v_mul_f32_e32 v212, v16, v164
	v_mul_f32_e32 v213, v17, v165
	v_mul_f32_e32 v214, v18, v244
	v_mul_f32_e32 v215, v19, v245
	s_waitcnt lgkmcnt(1)
	v_add_f32_e32 v164, v158, v250
	v_add_f32_e32 v165, v158, v251
	v_add_f32_e32 v244, v158, v252
	v_add_f32_e32 v245, v158, v253
	v_exp_f32_e32 v164, v164
	v_exp_f32_e32 v165, v165
	v_exp_f32_e32 v244, v244
	v_exp_f32_e32 v245, v245
	ds_read_b128 v[250:253], v161 offset:4320
	v_mul_f32_e32 v216, v20, v164
	v_mul_f32_e32 v217, v21, v165
	v_mul_f32_e32 v218, v22, v244
	v_mul_f32_e32 v219, v23, v245
	s_waitcnt vmcnt(16)
	v_add_f32_e32 v169, v212, v159
	v_add_f32_e32 v183, v213, v159
	v_cmp_eq_u32_e32 vcc, 0, v160
	v_cmp_eq_u32_e64 s[100:101], 1, v160
	s_nop 0
	v_cndmask_b32_e32 v169, 0, v169, vcc
	v_cndmask_b32_e64 v183, 0, v183, s[100:101]
	v_cmp_lt_i32_e32 vcc, 0, v160
	v_cmp_lt_i32_e64 s[100:101], 1, v160
	s_nop 0
	v_cndmask_b32_e32 v212, v169, v212, vcc
	v_cndmask_b32_e64 v213, v183, v213, s[100:101]
	v_add_f32_e32 v169, v214, v159
	v_add_f32_e32 v183, v215, v159
	v_cmp_eq_u32_e32 vcc, 2, v160
	v_cmp_eq_u32_e64 s[100:101], 3, v160
	s_nop 0
	v_cndmask_b32_e32 v169, 0, v169, vcc
	v_cndmask_b32_e64 v183, 0, v183, s[100:101]
	v_cmp_lt_i32_e32 vcc, 2, v160
	v_cmp_lt_i32_e64 s[100:101], 3, v160
	s_nop 0
	v_cndmask_b32_e32 v214, v169, v214, vcc
	v_cndmask_b32_e64 v215, v183, v215, s[100:101]
	v_add_f32_e32 v169, v216, v159
	v_add_f32_e32 v183, v217, v159
	v_cmp_eq_u32_e32 vcc, 8, v160
	v_cmp_eq_u32_e64 s[100:101], 9, v160
	s_nop 0
	v_cndmask_b32_e32 v169, 0, v169, vcc
	v_cndmask_b32_e64 v183, 0, v183, s[100:101]
	v_cmp_lt_i32_e32 vcc, 8, v160
	v_cmp_lt_i32_e64 s[100:101], 9, v160
	s_nop 0
	v_cndmask_b32_e32 v216, v169, v216, vcc
	v_cndmask_b32_e64 v217, v183, v217, s[100:101]
	v_add_f32_e32 v169, v218, v159
	v_add_f32_e32 v183, v219, v159
	v_cmp_eq_u32_e32 vcc, 10, v160
	v_cmp_eq_u32_e64 s[100:101], 11, v160
	s_nop 0
	v_cndmask_b32_e32 v169, 0, v169, vcc
	v_cndmask_b32_e64 v183, 0, v183, s[100:101]
	v_cmp_lt_i32_e32 vcc, 10, v160
	v_cmp_lt_i32_e64 s[100:101], 11, v160
	s_nop 0
	v_cndmask_b32_e32 v218, v169, v218, vcc
	v_cndmask_b32_e64 v219, v183, v219, s[100:101]
	v_cvt_pk_bf16_f32 v212, v212, v213
	v_cvt_pk_bf16_f32 v213, v214, v215
	v_cvt_pk_bf16_f32 v214, v216, v217
	v_cvt_pk_bf16_f32 v215, v218, v219
	s_nop 0
	s_waitcnt vmcnt(12)
	v_mfma_f32_32x32x16_bf16 v[64:79], v[192:195], v[212:215], v[64:79]
	s_waitcnt lgkmcnt(1)
	v_add_f32_e32 v164, v158, v236
	v_add_f32_e32 v165, v158, v237
	v_add_f32_e32 v244, v158, v238
	v_add_f32_e32 v245, v158, v239
	v_exp_f32_e32 v164, v164
	v_exp_f32_e32 v165, v165
	v_exp_f32_e32 v244, v244
	v_exp_f32_e32 v245, v245
	v_mul_f32_e32 v212, v24, v164
	v_mul_f32_e32 v213, v25, v165
	v_mul_f32_e32 v214, v26, v244
	v_mul_f32_e32 v215, v27, v245
	s_waitcnt lgkmcnt(0)
	v_add_f32_e32 v164, v158, v250
	v_add_f32_e32 v165, v158, v251
	v_add_f32_e32 v244, v158, v252
	v_add_f32_e32 v245, v158, v253
	v_exp_f32_e32 v164, v164
	v_exp_f32_e32 v165, v165
	v_exp_f32_e32 v244, v244
	v_exp_f32_e32 v245, v245
	v_mul_f32_e32 v216, v28, v164
	v_mul_f32_e32 v217, v29, v165
	v_mul_f32_e32 v218, v30, v244
	v_mul_f32_e32 v219, v31, v245
	v_add_f32_e32 v169, v212, v159
	v_add_f32_e32 v183, v213, v159
	v_cmp_eq_u32_e32 vcc, 16, v160
	v_cmp_eq_u32_e64 s[100:101], 17, v160
	s_nop 0
	v_cndmask_b32_e32 v169, 0, v169, vcc
	v_cndmask_b32_e64 v183, 0, v183, s[100:101]
	v_cmp_lt_i32_e32 vcc, 16, v160
	v_cmp_lt_i32_e64 s[100:101], 17, v160
	s_nop 0
	v_cndmask_b32_e32 v212, v169, v212, vcc
	v_cndmask_b32_e64 v213, v183, v213, s[100:101]
	v_add_f32_e32 v169, v214, v159
	v_add_f32_e32 v183, v215, v159
	v_cmp_eq_u32_e32 vcc, 18, v160
	v_cmp_eq_u32_e64 s[100:101], 19, v160
	s_nop 0
	v_cndmask_b32_e32 v169, 0, v169, vcc
	v_cndmask_b32_e64 v183, 0, v183, s[100:101]
	v_cmp_lt_i32_e32 vcc, 18, v160
	v_cmp_lt_i32_e64 s[100:101], 19, v160
	s_nop 0
	v_cndmask_b32_e32 v214, v169, v214, vcc
	v_cndmask_b32_e64 v215, v183, v215, s[100:101]
	v_add_f32_e32 v169, v216, v159
	v_add_f32_e32 v183, v217, v159
	v_cmp_eq_u32_e32 vcc, 24, v160
	v_cmp_eq_u32_e64 s[100:101], 25, v160
	s_nop 0
	v_cndmask_b32_e32 v169, 0, v169, vcc
	v_cndmask_b32_e64 v183, 0, v183, s[100:101]
	v_cmp_lt_i32_e32 vcc, 24, v160
	v_cmp_lt_i32_e64 s[100:101], 25, v160
	s_nop 0
	v_cndmask_b32_e32 v216, v169, v216, vcc
	v_cndmask_b32_e64 v217, v183, v217, s[100:101]
	v_add_f32_e32 v169, v218, v159
	v_add_f32_e32 v183, v219, v159
	v_cmp_eq_u32_e32 vcc, 26, v160
	v_cmp_eq_u32_e64 s[100:101], 27, v160
	s_nop 0
	v_cndmask_b32_e32 v169, 0, v169, vcc
	v_cndmask_b32_e64 v183, 0, v183, s[100:101]
	v_cmp_lt_i32_e32 vcc, 26, v160
	v_cmp_lt_i32_e64 s[100:101], 27, v160
	s_nop 0
	v_cndmask_b32_e32 v218, v169, v218, vcc
	v_cndmask_b32_e64 v219, v183, v219, s[100:101]
	s_cmp_eq_u32 s94, 0x1c000
	s_cselect_b32 s100, 0, 4
	s_add_u32 s84, s84, s100
	s_addc_u32 s85, s85, 0
	v_mov_b32_e32 v164, 0
	global_load_dword v159, v164, s[84:85]
	v_cvt_pk_bf16_f32 v212, v212, v213
	v_cvt_pk_bf16_f32 v213, v214, v215
	v_cvt_pk_bf16_f32 v214, v216, v217
	v_cvt_pk_bf16_f32 v215, v218, v219
	s_nop 0
	s_nop 0
	v_mfma_f32_32x32x16_bf16 v[64:79], v[198:201], v[212:215], v[64:79]
	global_load_dwordx2 v[192:193], v[184:185], off offset:64
	global_load_dwordx2 v[194:195], v[184:185], off offset:80
	global_load_dwordx2 v[198:199], v[184:185], off offset:96
	global_load_dwordx2 v[200:201], v[184:185], off offset:112
	s_nop 10
	ds_read_b64 v[216:217], v162 offset:0
	s_waitcnt lgkmcnt(0)
; #define LAS __attribute__((address_space(3)))
; __device__ __forceinline__ float bflo(unsigned u) { return __uint_as_float(u << 16); }
; __device__ __forceinline__ float bfhi(unsigned u) { return __uint_as_float(u & 0xffff0000u); }
; __device__ __forceinline__ f32x16 mfma32(bf16x8 a, bf16x8 b, f32x16 c) { return __builtin_amdgcn_mfma_f32_32x32x16_bf16(a, b, c, 0, 0, 0); }
; __device__ __forceinline__ void phase_ssd_y(const PT& p, LAS unsigned char* lds, int tid, int lane, int wave) {
;     ...
;             const bf16* pp = PV + ((size_t)(bc * 32 + hh) * 64 + pb * 32 + r32) * 128 + 8 * h;
; #pragma unroll
;             for (int st = 0; st < 8; ++st) acc = mfma32(ld_frag16(pp + 16 * st), cf[st], acc);
;     ...
; #pragma unroll
;             for (int qd = 0; qd < 4; ++qd) {
;                 LAS u32x2* yp = (LAS u32x2*)(tile + l * SY_TP + (r * 64 + pb * 32 + 8 * qd + 4 * h) * 2); const u32x2 zz = *yp;
;                 const float y0 = acc[4 * qd] * bflo(zz.x), y1 = acc[4 * qd + 1] * bfhi(zz.x);
;                 const float y2 = acc[4 * qd + 2] * bflo(zz.y), y3 = acc[4 * qd + 3] * bfhi(zz.y);
;                 ssq += (y0 * y0 + y1 * y1) + (y2 * y2 + y3 * y3);
;                 u32x2 w; w.x = pk2(y0, y1); w.y = pk2(y2, y3); *yp = w;
;             }
;         }
	v_lshlrev_b32_e32 v169, 16, v216
	v_and_b32_e32 v183, 0xffff0000, v216
	v_lshlrev_b32_e32 v254, 16, v217
	v_and_b32_e32 v255, 0xffff0000, v217
	v_mul_f32_e32 v169, v64, v169
	v_mul_f32_e32 v183, v65, v183
	v_mul_f32_e32 v254, v66, v254
	v_mul_f32_e32 v255, v67, v255
	v_mul_f32_e32 v164, v169, v169
	v_mul_f32_e32 v165, v254, v254
	v_fmac_f32_e32 v164, v183, v183
	v_fmac_f32_e32 v165, v255, v255
	v_cvt_pk_bf16_f32 v216, v169, v183
	v_cvt_pk_bf16_f32 v217, v254, v255
	v_add_f32_e32 v164, v164, v165
	ds_write_b64 v162, v[216:217] offset:0
	v_add_f32_e32 v126, v126, v164
	ds_read_b64 v[216:217], v162 offset:16
	s_waitcnt lgkmcnt(0)
	v_lshlrev_b32_e32 v169, 16, v216
	v_and_b32_e32 v183, 0xffff0000, v216
	v_lshlrev_b32_e32 v254, 16, v217
	v_and_b32_e32 v255, 0xffff0000, v217
	v_mul_f32_e32 v169, v68, v169
	v_mul_f32_e32 v183, v69, v183
	v_mul_f32_e32 v254, v70, v254
	v_mul_f32_e32 v255, v71, v255
	v_mul_f32_e32 v164, v169, v169
	v_mul_f32_e32 v165, v254, v254
	v_fmac_f32_e32 v164, v183, v183
	v_fmac_f32_e32 v165, v255, v255
	v_cvt_pk_bf16_f32 v216, v169, v183
	v_cvt_pk_bf16_f32 v217, v254, v255
	v_add_f32_e32 v164, v164, v165
	ds_write_b64 v162, v[216:217] offset:16
	v_add_f32_e32 v126, v126, v164
	ds_read_b64 v[216:217], v162 offset:32
	s_waitcnt lgkmcnt(0)
	v_lshlrev_b32_e32 v169, 16, v216
	v_and_b32_e32 v183, 0xffff0000, v216
	v_lshlrev_b32_e32 v254, 16, v217
	v_and_b32_e32 v255, 0xffff0000, v217
	v_mul_f32_e32 v169, v72, v169
	v_mul_f32_e32 v183, v73, v183
	v_mul_f32_e32 v254, v74, v254
	v_mul_f32_e32 v255, v75, v255
	v_mul_f32_e32 v164, v169, v169
	v_mul_f32_e32 v165, v254, v254
	v_fmac_f32_e32 v164, v183, v183
	v_fmac_f32_e32 v165, v255, v255
	v_cvt_pk_bf16_f32 v216, v169, v183
	v_cvt_pk_bf16_f32 v217, v254, v255
	v_add_f32_e32 v164, v164, v165
	ds_write_b64 v162, v[216:217] offset:32
	v_add_f32_e32 v126, v126, v164
	ds_read_b64 v[216:217], v162 offset:48
	s_waitcnt lgkmcnt(0)
	v_lshlrev_b32_e32 v169, 16, v216
	v_and_b32_e32 v183, 0xffff0000, v216
	v_lshlrev_b32_e32 v254, 16, v217
	v_and_b32_e32 v255, 0xffff0000, v217
	v_mul_f32_e32 v169, v76, v169
	v_mul_f32_e32 v183, v77, v183
	v_mul_f32_e32 v254, v78, v254
	v_mul_f32_e32 v255, v79, v255
	v_mul_f32_e32 v164, v169, v169
	v_mul_f32_e32 v165, v254, v254
	v_fmac_f32_e32 v164, v183, v183
	v_fmac_f32_e32 v165, v255, v255
	v_cvt_pk_bf16_f32 v216, v169, v183
	v_cvt_pk_bf16_f32 v217, v254, v255
	v_add_f32_e32 v164, v164, v165
	ds_write_b64 v162, v[216:217] offset:48
	v_add_f32_e32 v126, v126, v164
	v_add_u32_e32 v161, 0x200, v161
	v_add_u32_e32 v141, 0x200, v141
	v_add_u32_e32 v162, 0x80, v162
	v_mov_b32_e32 v206, v184
	v_mov_b32_e32 v207, v185
	v_add_co_u32_e32 v184, vcc, 0x4000, v184
	s_nop 1
	v_addc_co_u32_e32 v185, vcc, 0, v185, vcc
	s_add_u32 s94, s94, 0x4000
	s_cmp_eq_u32 s94, 0x20000
	s_cbranch_scc0 .Lp5v1_head
	s_branch .Lp5v_exit
.Lp5v0:
	v_lshl_add_u64 v[212:213], v[142:143], 0, s[94:95]
	v_lshl_add_u64 v[206:207], v[144:145], 0, s[94:95]
	v_mov_b32_e32 v164, 0
	v_add_co_u32_e32 v206, vcc, 0x1a900000, v206
	s_nop 1
	v_addc_co_u32_e32 v207, vcc, 0, v207, vcc
	v_add_co_u32_e32 v184, vcc, 0x4000, v206
	s_nop 1
	v_addc_co_u32_e32 v185, vcc, 0, v207, vcc
	global_load_dword v159, v164, s[84:85]
	global_load_dwordx4 v[170:173], v[212:213], off
	global_load_dwordx4 v[174:177], v[212:213], off offset:32
	global_load_dwordx4 v[178:181], v[212:213], off offset:64
	global_load_dwordx4 v[220:223], v[212:213], off offset:96
	global_load_dwordx4 v[224:227], v[212:213], off offset:128
	global_load_dwordx4 v[228:231], v[212:213], off offset:160
	global_load_dwordx4 v[232:235], v[212:213], off offset:192
	global_load_dwordx4 v[208:211], v[212:213], off offset:224
	global_load_dwordx2 v[150:151], v[206:207], off offset:0
	global_load_dwordx2 v[152:153], v[206:207], off offset:16
	global_load_dwordx2 v[154:155], v[206:207], off offset:32
	global_load_dwordx2 v[156:157], v[206:207], off offset:48
	s_waitcnt vmcnt(0)
.Lp5v0_head:
	s_add_u32 s100, s94, 0x4000
	s_mov_b32 s101, 0
	ds_read_b32 v158, v141
	v_lshl_add_u64 v[212:213], v[142:143], 0, s[100:101]
	s_waitcnt vmcnt(12)
	v_mfma_f32_32x32x16_bf16 v[64:79], v[170:173], v[80:83], 0
	global_load_dwordx4 v[170:173], v[212:213], off
	s_waitcnt vmcnt(12)
	v_mfma_f32_32x32x16_bf16 v[64:79], v[174:177], v[84:87], v[64:79]
	global_load_dwordx4 v[174:177], v[212:213], off offset:32
	s_waitcnt vmcnt(12)
	v_mfma_f32_32x32x16_bf16 v[64:79], v[178:181], v[88:91], v[64:79]
	global_load_dwordx4 v[178:181], v[212:213], off offset:64
	s_waitcnt vmcnt(12)
	v_mfma_f32_32x32x16_bf16 v[64:79], v[220:223], v[92:95], v[64:79]
	global_load_dwordx4 v[220:223], v[212:213], off offset:96
	s_waitcnt vmcnt(12)
	v_mfma_f32_32x32x16_bf16 v[64:79], v[224:227], v[96:99], v[64:79]
	global_load_dwordx4 v[224:227], v[212:213], off offset:128
	s_waitcnt vmcnt(12)
	v_mfma_f32_32x32x16_bf16 v[64:79], v[228:231], v[100:103], v[64:79]
	global_load_dwordx4 v[228:231], v[212:213], off offset:160
	s_waitcnt vmcnt(12)
	v_mfma_f32_32x32x16_bf16 v[64:79], v[232:235], v[104:107], v[64:79]
	global_load_dwordx4 v[232:235], v[212:213], off offset:192
	s_waitcnt vmcnt(12)
	v_mfma_f32_32x32x16_bf16 v[64:79], v[208:211], v[108:111], v[64:79]
	global_load_dwordx4 v[208:211], v[212:213], off offset:224
	s_waitcnt lgkmcnt(0)
	v_mul_f32_e32 v164, 0x3fb8aa3b, v158
	v_exp_f32_e32 v165, v164
	v_mov_b32_e32 v158, v164
	s_nop 8
	v_mul_f32_e32 v64, v165, v64
	v_mul_f32_e32 v65, v165, v65
	v_mul_f32_e32 v66, v165, v66
	v_mul_f32_e32 v67, v165, v67
	v_mul_f32_e32 v68, v165, v68
	v_mul_f32_e32 v69, v165, v69
	v_mul_f32_e32 v70, v165, v70
	v_mul_f32_e32 v71, v165, v71
	v_mul_f32_e32 v72, v165, v72
	v_mul_f32_e32 v73, v165, v73
	v_mul_f32_e32 v74, v165, v74
	v_mul_f32_e32 v75, v165, v75
	v_mul_f32_e32 v76, v165, v76
	v_mul_f32_e32 v77, v165, v77
	v_mul_f32_e32 v78, v165, v78
	v_mul_f32_e32 v79, v165, v79
	ds_read_b128 v[236:239], v161 offset:4096
	ds_read_b128 v[250:253], v161 offset:4128
	s_waitcnt lgkmcnt(1)
; #define LAS __attribute__((address_space(3)))
; __device__ __forceinline__ f32x16 mfma32(bf16x8 a, bf16x8 b, f32x16 c) { return __builtin_amdgcn_mfma_f32_32x32x16_bf16(a, b, c, 0, 0, 0); }
; __device__ __forceinline__ void phase_ssd_y(const PT& p, LAS unsigned char* lds, int tid, int lane, int wave) {
;     ...
;             for (int sb = 0; sb < 4; ++sb) {
;                 if (sb <= lb) {
;                     f32x16 mm;
; #pragma unroll
;                     for (int qd = 0; qd < 4; ++qd) {
;                         const int s0 = sb * 32 + 8 * qd + 4 * h;
;                         const f32x4 as = *(const LAS f32x4*)(acum + r * 128 + s0), ds = *(const LAS f32x4*)(dtt + r * 128 + s0);
; #pragma unroll
;                         for (int j = 0; j < 4; ++j) { const float v = X[sb][4 * qd + j] * __expf(al - as[j]) * ds[j]; mm[4 * qd + j] = (s0 + j < l) ? v : ((s0 + j == l) ? v + dsk : 0.f); }
;                     }
; #pragma unroll
;                     for (int s2 = 0; s2 < 2; ++s2) acc = mfma32(ld_frag8x2(xrow + sb * 32 + 16 * s2), pack_frag(mm, s2), acc);
	v_add_f32_e32 v164, v158, v236
	v_add_f32_e32 v165, v158, v237
	v_add_f32_e32 v244, v158, v238
	v_add_f32_e32 v245, v158, v239
	v_exp_f32_e32 v164, v164
	v_exp_f32_e32 v165, v165
	v_exp_f32_e32 v244, v244
	v_exp_f32_e32 v245, v245
	ds_read_b128 v[236:239], v161 offset:4160
	v_mul_f32_e32 v212, v0, v164
	v_mul_f32_e32 v213, v1, v165
	v_mul_f32_e32 v214, v2, v244
	v_mul_f32_e32 v215, v3, v245
	s_waitcnt lgkmcnt(1)
	v_add_f32_e32 v164, v158, v250
	v_add_f32_e32 v165, v158, v251
	v_add_f32_e32 v244, v158, v252
	v_add_f32_e32 v245, v158, v253
	v_exp_f32_e32 v164, v164
	v_exp_f32_e32 v165, v165
	v_exp_f32_e32 v244, v244
	v_exp_f32_e32 v245, v245
	ds_read_b128 v[250:253], v161 offset:4192
	v_mul_f32_e32 v216, v4, v164
	v_mul_f32_e32 v217, v5, v165
	v_mul_f32_e32 v218, v6, v244
	v_mul_f32_e32 v219, v7, v245
	s_waitcnt vmcnt(12)
	v_add_f32_e32 v169, v212, v159
	v_add_f32_e32 v183, v213, v159
	v_cmp_eq_u32_e32 vcc, 0, v160
	v_cmp_eq_u32_e64 s[100:101], 1, v160
	s_nop 0
	v_cndmask_b32_e32 v169, 0, v169, vcc
	v_cndmask_b32_e64 v183, 0, v183, s[100:101]
	v_cmp_lt_i32_e32 vcc, 0, v160
	v_cmp_lt_i32_e64 s[100:101], 1, v160
	s_nop 0
	v_cndmask_b32_e32 v212, v169, v212, vcc
	v_cndmask_b32_e64 v213, v183, v213, s[100:101]
	v_add_f32_e32 v169, v214, v159
	v_add_f32_e32 v183, v215, v159
	v_cmp_eq_u32_e32 vcc, 2, v160
	v_cmp_eq_u32_e64 s[100:101], 3, v160
	s_nop 0
	v_cndmask_b32_e32 v169, 0, v169, vcc
	v_cndmask_b32_e64 v183, 0, v183, s[100:101]
	v_cmp_lt_i32_e32 vcc, 2, v160
	v_cmp_lt_i32_e64 s[100:101], 3, v160
	s_nop 0
	v_cndmask_b32_e32 v214, v169, v214, vcc
	v_cndmask_b32_e64 v215, v183, v215, s[100:101]
	v_add_f32_e32 v169, v216, v159
	v_add_f32_e32 v183, v217, v159
	v_cmp_eq_u32_e32 vcc, 8, v160
	v_cmp_eq_u32_e64 s[100:101], 9, v160
	s_nop 0
	v_cndmask_b32_e32 v169, 0, v169, vcc
	v_cndmask_b32_e64 v183, 0, v183, s[100:101]
	v_cmp_lt_i32_e32 vcc, 8, v160
	v_cmp_lt_i32_e64 s[100:101], 9, v160
	s_nop 0
	v_cndmask_b32_e32 v216, v169, v216, vcc
	v_cndmask_b32_e64 v217, v183, v217, s[100:101]
	v_add_f32_e32 v169, v218, v159
	v_add_f32_e32 v183, v219, v159
	v_cmp_eq_u32_e32 vcc, 10, v160
	v_cmp_eq_u32_e64 s[100:101], 11, v160
	s_nop 0
	v_cndmask_b32_e32 v169, 0, v169, vcc
	v_cndmask_b32_e64 v183, 0, v183, s[100:101]
	v_cmp_lt_i32_e32 vcc, 10, v160
	v_cmp_lt_i32_e64 s[100:101], 11, v160
	s_nop 0
	v_cndmask_b32_e32 v218, v169, v218, vcc
	v_cndmask_b32_e64 v219, v183, v219, s[100:101]
	v_cvt_pk_bf16_f32 v212, v212, v213
	v_cvt_pk_bf16_f32 v213, v214, v215
	v_cvt_pk_bf16_f32 v214, v216, v217
	v_cvt_pk_bf16_f32 v215, v218, v219
	s_nop 0
	s_waitcnt vmcnt(8)
	v_mfma_f32_32x32x16_bf16 v[64:79], v[150:153], v[212:215], v[64:79]
	s_waitcnt lgkmcnt(1)
	v_add_f32_e32 v164, v158, v236
	v_add_f32_e32 v165, v158, v237
	v_add_f32_e32 v244, v158, v238
	v_add_f32_e32 v245, v158, v239
	v_exp_f32_e32 v164, v164
	v_exp_f32_e32 v165, v165
	v_exp_f32_e32 v244, v244
	v_exp_f32_e32 v245, v245
	v_mul_f32_e32 v212, v8, v164
	v_mul_f32_e32 v213, v9, v165
	v_mul_f32_e32 v214, v10, v244
	v_mul_f32_e32 v215, v11, v245
	s_waitcnt lgkmcnt(0)
; #define LAS __attribute__((address_space(3)))
; __device__ __forceinline__ float bflo(unsigned u) { return __uint_as_float(u << 16); }
; __device__ __forceinline__ float bfhi(unsigned u) { return __uint_as_float(u & 0xffff0000u); }
; __device__ __forceinline__ f32x16 mfma32(bf16x8 a, bf16x8 b, f32x16 c) { return __builtin_amdgcn_mfma_f32_32x32x16_bf16(a, b, c, 0, 0, 0); }
; __device__ __forceinline__ void phase_ssd_y(const PT& p, LAS unsigned char* lds, int tid, int lane, int wave) {
;     ...
;                     for (int qd = 0; qd < 4; ++qd) {
;                         const int s0 = sb * 32 + 8 * qd + 4 * h;
;                         const f32x4 as = *(const LAS f32x4*)(acum + r * 128 + s0), ds = *(const LAS f32x4*)(dtt + r * 128 + s0);
; #pragma unroll
;                         for (int j = 0; j < 4; ++j) { const float v = X[sb][4 * qd + j] * __expf(al - as[j]) * ds[j]; mm[4 * qd + j] = (s0 + j < l) ? v : ((s0 + j == l) ? v + dsk : 0.f); }
;                     }
; #pragma unroll
;                     for (int s2 = 0; s2 < 2; ++s2) acc = mfma32(ld_frag8x2(xrow + sb * 32 + 16 * s2), pack_frag(mm, s2), acc);
;                 }
;             }
; #pragma unroll
;             for (int qd = 0; qd < 4; ++qd) {
;                 LAS u32x2* yp = (LAS u32x2*)(tile + l * SY_TP + (r * 64 + pb * 32 + 8 * qd + 4 * h) * 2); const u32x2 zz = *yp;
;                 const float y0 = acc[4 * qd] * bflo(zz.x), y1 = acc[4 * qd + 1] * bfhi(zz.x);
;                 const float y2 = acc[4 * qd + 2] * bflo(zz.y), y3 = acc[4 * qd + 3] * bfhi(zz.y);
;                 ssq += (y0 * y0 + y1 * y1) + (y2 * y2 + y3 * y3);
;                 u32x2 w; w.x = pk2(y0, y1); w.y = pk2(y2, y3); *yp = w;
;             }
	v_add_f32_e32 v164, v158, v250
	v_add_f32_e32 v165, v158, v251
	v_add_f32_e32 v244, v158, v252
	v_add_f32_e32 v245, v158, v253
	v_exp_f32_e32 v164, v164
	v_exp_f32_e32 v165, v165
	v_exp_f32_e32 v244, v244
	v_exp_f32_e32 v245, v245
	v_mul_f32_e32 v216, v12, v164
	v_mul_f32_e32 v217, v13, v165
	v_mul_f32_e32 v218, v14, v244
	v_mul_f32_e32 v219, v15, v245
	v_add_f32_e32 v169, v212, v159
	v_add_f32_e32 v183, v213, v159
	v_cmp_eq_u32_e32 vcc, 16, v160
	v_cmp_eq_u32_e64 s[100:101], 17, v160
	s_nop 0
	v_cndmask_b32_e32 v169, 0, v169, vcc
	v_cndmask_b32_e64 v183, 0, v183, s[100:101]
	v_cmp_lt_i32_e32 vcc, 16, v160
	v_cmp_lt_i32_e64 s[100:101], 17, v160
	s_nop 0
	v_cndmask_b32_e32 v212, v169, v212, vcc
	v_cndmask_b32_e64 v213, v183, v213, s[100:101]
	v_add_f32_e32 v169, v214, v159
	v_add_f32_e32 v183, v215, v159
	v_cmp_eq_u32_e32 vcc, 18, v160
	v_cmp_eq_u32_e64 s[100:101], 19, v160
	s_nop 0
	v_cndmask_b32_e32 v169, 0, v169, vcc
	v_cndmask_b32_e64 v183, 0, v183, s[100:101]
	v_cmp_lt_i32_e32 vcc, 18, v160
	v_cmp_lt_i32_e64 s[100:101], 19, v160
	s_nop 0
	v_cndmask_b32_e32 v214, v169, v214, vcc
	v_cndmask_b32_e64 v215, v183, v215, s[100:101]
	v_add_f32_e32 v169, v216, v159
	v_add_f32_e32 v183, v217, v159
	v_cmp_eq_u32_e32 vcc, 24, v160
	v_cmp_eq_u32_e64 s[100:101], 25, v160
	s_nop 0
	v_cndmask_b32_e32 v169, 0, v169, vcc
	v_cndmask_b32_e64 v183, 0, v183, s[100:101]
	v_cmp_lt_i32_e32 vcc, 24, v160
	v_cmp_lt_i32_e64 s[100:101], 25, v160
	s_nop 0
	v_cndmask_b32_e32 v216, v169, v216, vcc
	v_cndmask_b32_e64 v217, v183, v217, s[100:101]
	v_add_f32_e32 v169, v218, v159
	v_add_f32_e32 v183, v219, v159
	v_cmp_eq_u32_e32 vcc, 26, v160
	v_cmp_eq_u32_e64 s[100:101], 27, v160
	s_nop 0
	v_cndmask_b32_e32 v169, 0, v169, vcc
	v_cndmask_b32_e64 v183, 0, v183, s[100:101]
	v_cmp_lt_i32_e32 vcc, 26, v160
	v_cmp_lt_i32_e64 s[100:101], 27, v160
	s_nop 0
	v_cndmask_b32_e32 v218, v169, v218, vcc
	v_cndmask_b32_e64 v219, v183, v219, s[100:101]
	s_cmp_eq_u32 s94, 0x1c000
	s_cselect_b32 s100, 0, 4
	s_add_u32 s84, s84, s100
	s_addc_u32 s85, s85, 0
	v_mov_b32_e32 v164, 0
	global_load_dword v159, v164, s[84:85]
	v_cvt_pk_bf16_f32 v212, v212, v213
	v_cvt_pk_bf16_f32 v213, v214, v215
	v_cvt_pk_bf16_f32 v214, v216, v217
	v_cvt_pk_bf16_f32 v215, v218, v219
	s_nop 0
	s_nop 0
	v_mfma_f32_32x32x16_bf16 v[64:79], v[154:157], v[212:215], v[64:79]
	global_load_dwordx2 v[150:151], v[184:185], off offset:0
	global_load_dwordx2 v[152:153], v[184:185], off offset:16
	global_load_dwordx2 v[154:155], v[184:185], off offset:32
	global_load_dwordx2 v[156:157], v[184:185], off offset:48
	s_nop 10
	ds_read_b64 v[216:217], v162 offset:0
	s_waitcnt lgkmcnt(0)
	v_lshlrev_b32_e32 v169, 16, v216
	v_and_b32_e32 v183, 0xffff0000, v216
	v_lshlrev_b32_e32 v254, 16, v217
	v_and_b32_e32 v255, 0xffff0000, v217
	v_mul_f32_e32 v169, v64, v169
	v_mul_f32_e32 v183, v65, v183
	v_mul_f32_e32 v254, v66, v254
	v_mul_f32_e32 v255, v67, v255
	v_mul_f32_e32 v164, v169, v169
	v_mul_f32_e32 v165, v254, v254
	v_fmac_f32_e32 v164, v183, v183
	v_fmac_f32_e32 v165, v255, v255
	v_cvt_pk_bf16_f32 v216, v169, v183
	v_cvt_pk_bf16_f32 v217, v254, v255
	v_add_f32_e32 v164, v164, v165
	ds_write_b64 v162, v[216:217] offset:0
	v_add_f32_e32 v126, v126, v164
	ds_read_b64 v[216:217], v162 offset:16
	s_waitcnt lgkmcnt(0)
	v_lshlrev_b32_e32 v169, 16, v216
	v_and_b32_e32 v183, 0xffff0000, v216
	v_lshlrev_b32_e32 v254, 16, v217
	v_and_b32_e32 v255, 0xffff0000, v217
	v_mul_f32_e32 v169, v68, v169
	v_mul_f32_e32 v183, v69, v183
	v_mul_f32_e32 v254, v70, v254
	v_mul_f32_e32 v255, v71, v255
	v_mul_f32_e32 v164, v169, v169
	v_mul_f32_e32 v165, v254, v254
	v_fmac_f32_e32 v164, v183, v183
	v_fmac_f32_e32 v165, v255, v255
	v_cvt_pk_bf16_f32 v216, v169, v183
	v_cvt_pk_bf16_f32 v217, v254, v255
	v_add_f32_e32 v164, v164, v165
	ds_write_b64 v162, v[216:217] offset:16
	v_add_f32_e32 v126, v126, v164
	ds_read_b64 v[216:217], v162 offset:32
	s_waitcnt lgkmcnt(0)
	v_lshlrev_b32_e32 v169, 16, v216
	v_and_b32_e32 v183, 0xffff0000, v216
	v_lshlrev_b32_e32 v254, 16, v217
	v_and_b32_e32 v255, 0xffff0000, v217
	v_mul_f32_e32 v169, v72, v169
	v_mul_f32_e32 v183, v73, v183
	v_mul_f32_e32 v254, v74, v254
	v_mul_f32_e32 v255, v75, v255
	v_mul_f32_e32 v164, v169, v169
	v_mul_f32_e32 v165, v254, v254
	v_fmac_f32_e32 v164, v183, v183
	v_fmac_f32_e32 v165, v255, v255
	v_cvt_pk_bf16_f32 v216, v169, v183
	v_cvt_pk_bf16_f32 v217, v254, v255
	v_add_f32_e32 v164, v164, v165
	ds_write_b64 v162, v[216:217] offset:32
	v_add_f32_e32 v126, v126, v164
	ds_read_b64 v[216:217], v162 offset:48
	s_waitcnt lgkmcnt(0)
	v_lshlrev_b32_e32 v169, 16, v216
	v_and_b32_e32 v183, 0xffff0000, v216
	v_lshlrev_b32_e32 v254, 16, v217
	v_and_b32_e32 v255, 0xffff0000, v217
	v_mul_f32_e32 v169, v76, v169
	v_mul_f32_e32 v183, v77, v183
	v_mul_f32_e32 v254, v78, v254
	v_mul_f32_e32 v255, v79, v255
	v_mul_f32_e32 v164, v169, v169
	v_mul_f32_e32 v165, v254, v254
	v_fmac_f32_e32 v164, v183, v183
	v_fmac_f32_e32 v165, v255, v255
	v_cvt_pk_bf16_f32 v216, v169, v183
	v_cvt_pk_bf16_f32 v217, v254, v255
	v_add_f32_e32 v164, v164, v165
	ds_write_b64 v162, v[216:217] offset:48
	v_add_f32_e32 v126, v126, v164
	v_add_u32_e32 v161, 0x200, v161
	v_add_u32_e32 v141, 0x200, v141
	v_add_u32_e32 v162, 0x80, v162
	v_mov_b32_e32 v206, v184
	v_mov_b32_e32 v207, v185
	v_add_co_u32_e32 v184, vcc, 0x4000, v184
	s_nop 1
	v_addc_co_u32_e32 v185, vcc, 0, v185, vcc
	s_add_u32 s94, s94, 0x4000
	s_cmp_eq_u32 s94, 0x20000
	s_cbranch_scc0 .Lp5v0_head
	s_branch .Lp5v_exit
.Lp5v_exit:
	s_waitcnt vmcnt(0) lgkmcnt(0)
	v_mov_b32_e32 v210, v126
